# LayerNorm phases: H and Y row stores (full 1 KiB row pieces) write-through sc1, so the grid barrier release behind each LN phase finds a clean L2
# speedup vs baseline: 1.0215x; 1.0055x over previous
.Lln0_loop:
	global_load_dwordx4 v[48:51], v[134:135], off offset:-4096
	global_load_dwordx4 v[52:55], v[134:135], off offset:-3072
	global_load_dwordx4 v[56:59], v[134:135], off offset:-2048
	global_load_dwordx4 v[60:63], v[134:135], off offset:-1024
	global_load_dwordx4 v[64:67], v[134:135], off
	global_load_dwordx4 v[68:71], v[134:135], off offset:1024
	global_load_dwordx4 v[72:75], v[134:135], off offset:2048
	global_load_dwordx4 v[76:79], v[134:135], off offset:3072
	v_lshl_add_u64 v[134:135], v[134:135], 0, v[156:157]
	global_load_dwordx4 v[32:35], v[128:129], off nt
	global_load_dwordx4 v[36:39], v[128:129], off offset:1024 nt
	global_load_dwordx4 v[40:43], v[128:129], off offset:2048 nt
	global_load_dwordx4 v[44:47], v[128:129], off offset:3072 nt
	v_lshl_add_u64 v[128:129], v[128:129], 0, v[152:153]
	s_waitcnt vmcnt(20)
	v_add_f32_e32 v112, v0, v1
	v_add_f32_e32 v113, v2, v3
	v_add_f32_e32 v114, v4, v5
	v_add_f32_e32 v115, v6, v7
	v_add_f32_e32 v116, v8, v9
	v_add_f32_e32 v117, v10, v11
	v_add_f32_e32 v118, v12, v13
	v_add_f32_e32 v119, v14, v15
	v_add_f32_e32 v112, v112, v116
	v_add_f32_e32 v113, v113, v117
	v_add_f32_e32 v114, v114, v118
	v_add_f32_e32 v115, v115, v119
	v_add_f32_e32 v112, v112, v113
	v_add_f32_e32 v114, v114, v115
	v_add_f32_e32 v112, v112, v114
	s_nop 1
	v_add_f32_dpp v112, v112, v112 quad_perm:[1,0,3,2] row_mask:0xf bank_mask:0xf
	s_nop 1
	v_add_f32_dpp v112, v112, v112 quad_perm:[2,3,0,1] row_mask:0xf bank_mask:0xf
	s_nop 1
	v_add_f32_dpp v112, v112, v112 row_half_mirror row_mask:0xf bank_mask:0xf
	s_nop 1
	v_add_f32_dpp v112, v112, v112 row_mirror row_mask:0xf bank_mask:0xf
	s_nop 1
	v_add_f32_dpp v112, v112, v112 row_bcast:15 row_mask:0xa bank_mask:0xf
	s_nop 1
	v_add_f32_dpp v112, v112, v112 row_bcast:31 row_mask:0xc bank_mask:0xf
	s_nop 1
	v_readlane_b32 s2, v112, 63
	s_nop 1
	v_fmac_f32_e32 v0, s2, v142
	v_fmac_f32_e32 v1, s2, v142
	v_fmac_f32_e32 v2, s2, v142
	v_fmac_f32_e32 v3, s2, v142
	v_fmac_f32_e32 v4, s2, v142
	v_fmac_f32_e32 v5, s2, v142
	v_fmac_f32_e32 v6, s2, v142
	v_fmac_f32_e32 v7, s2, v142
	v_fmac_f32_e32 v8, s2, v142
	v_fmac_f32_e32 v9, s2, v142
	v_fmac_f32_e32 v10, s2, v142
	v_fmac_f32_e32 v11, s2, v142
	v_fmac_f32_e32 v12, s2, v142
	v_fmac_f32_e32 v13, s2, v142
	v_fmac_f32_e32 v14, s2, v142
	v_fmac_f32_e32 v15, s2, v142
	v_mul_f32_e32 v112, v0, v0
	v_mul_f32_e32 v113, v1, v1
	v_mul_f32_e32 v114, v2, v2
	v_mul_f32_e32 v115, v3, v3
	v_fmac_f32_e32 v112, v4, v4
	v_fmac_f32_e32 v113, v5, v5
	v_fmac_f32_e32 v114, v6, v6
	v_fmac_f32_e32 v115, v7, v7
	v_fmac_f32_e32 v112, v8, v8
	v_fmac_f32_e32 v113, v9, v9
	v_fmac_f32_e32 v114, v10, v10
	v_fmac_f32_e32 v115, v11, v11
	v_fmac_f32_e32 v112, v12, v12
	v_fmac_f32_e32 v113, v13, v13
	v_fmac_f32_e32 v114, v14, v14
	v_fmac_f32_e32 v115, v15, v15
	v_add_f32_e32 v112, v112, v113
	v_add_f32_e32 v114, v114, v115
	v_add_f32_e32 v112, v112, v114
	s_nop 1
	v_add_f32_dpp v112, v112, v112 quad_perm:[1,0,3,2] row_mask:0xf bank_mask:0xf
	s_nop 1
	v_add_f32_dpp v112, v112, v112 quad_perm:[2,3,0,1] row_mask:0xf bank_mask:0xf
	s_nop 1
	v_add_f32_dpp v112, v112, v112 row_half_mirror row_mask:0xf bank_mask:0xf
	s_nop 1
	v_add_f32_dpp v112, v112, v112 row_mirror row_mask:0xf bank_mask:0xf
	s_nop 1
	v_add_f32_dpp v112, v112, v112 row_bcast:15 row_mask:0xa bank_mask:0xf
	s_nop 1
	v_add_f32_dpp v112, v112, v112 row_bcast:31 row_mask:0xc bank_mask:0xf
	s_nop 1
	v_readlane_b32 s2, v112, 63
	s_nop 1
	v_mov_b32_e32 v113, 0x358637bd
	v_mov_b32_e32 v114, 0x3a800000
	v_fmac_f32_e32 v113, s2, v114
	v_rsq_f32_e32 v115, v113
	v_mul_f32_e32 v113, 0.5, v113
	v_mul_f32_e32 v116, v115, v115
	v_mov_b32_e32 v117, 0x3fc00000
	v_fma_f32 v116, -v113, v116, v117
	v_mul_f32_e32 v144, v115, v116
	v_pk_mul_f32 v[0:1], v[0:1], v[144:145] op_sel_hi:[1,0]
	v_pk_mul_f32 v[2:3], v[2:3], v[144:145] op_sel_hi:[1,0]
	v_pk_mul_f32 v[4:5], v[4:5], v[144:145] op_sel_hi:[1,0]
	v_pk_mul_f32 v[6:7], v[6:7], v[144:145] op_sel_hi:[1,0]
	v_pk_mul_f32 v[8:9], v[8:9], v[144:145] op_sel_hi:[1,0]
	v_pk_mul_f32 v[10:11], v[10:11], v[144:145] op_sel_hi:[1,0]
	v_pk_mul_f32 v[12:13], v[12:13], v[144:145] op_sel_hi:[1,0]
	v_pk_mul_f32 v[14:15], v[14:15], v[144:145] op_sel_hi:[1,0]
	s_waitcnt vmcnt(4)
	v_pk_add_f32 v[64:65], v[64:65], 1.0 op_sel_hi:[1,0]
	v_pk_add_f32 v[66:67], v[66:67], 1.0 op_sel_hi:[1,0]
	v_pk_add_f32 v[68:69], v[68:69], 1.0 op_sel_hi:[1,0]
	v_pk_add_f32 v[70:71], v[70:71], 1.0 op_sel_hi:[1,0]
	v_pk_add_f32 v[72:73], v[72:73], 1.0 op_sel_hi:[1,0]
	v_pk_add_f32 v[74:75], v[74:75], 1.0 op_sel_hi:[1,0]
	v_pk_add_f32 v[76:77], v[76:77], 1.0 op_sel_hi:[1,0]
	v_pk_add_f32 v[78:79], v[78:79], 1.0 op_sel_hi:[1,0]
	v_pk_fma_f32 v[0:1], v[64:65], v[0:1], v[48:49]
	v_pk_fma_f32 v[2:3], v[66:67], v[2:3], v[50:51]
	v_pk_fma_f32 v[4:5], v[68:69], v[4:5], v[52:53]
	v_pk_fma_f32 v[6:7], v[70:71], v[6:7], v[54:55]
	v_pk_fma_f32 v[8:9], v[72:73], v[8:9], v[56:57]
	v_pk_fma_f32 v[10:11], v[74:75], v[10:11], v[58:59]
	v_pk_fma_f32 v[12:13], v[76:77], v[12:13], v[60:61]
	v_pk_fma_f32 v[14:15], v[78:79], v[14:15], v[62:63]
	v_cvt_pk_bf16_f32 v120, v0, v1
	v_cvt_pk_bf16_f32 v121, v2, v3
	v_cvt_pk_bf16_f32 v122, v4, v5
	v_cvt_pk_bf16_f32 v123, v6, v7
	v_cvt_pk_bf16_f32 v124, v8, v9
	v_cvt_pk_bf16_f32 v125, v10, v11
	v_cvt_pk_bf16_f32 v126, v12, v13
	v_cvt_pk_bf16_f32 v127, v14, v15
	v_cndmask_b32_e64 v112, v122, v120, s[40:41]
	v_cndmask_b32_e64 v113, v123, v121, s[40:41]
	v_cndmask_b32_e64 v114, v126, v124, s[40:41]
	v_cndmask_b32_e64 v115, v127, v125, s[40:41]
	v_mov_b32_dpp v116, v112 quad_perm:[1,0,3,2] row_mask:0xf bank_mask:0xf
	v_mov_b32_dpp v117, v113 quad_perm:[1,0,3,2] row_mask:0xf bank_mask:0xf
	v_mov_b32_dpp v118, v114 quad_perm:[1,0,3,2] row_mask:0xf bank_mask:0xf
	v_mov_b32_dpp v119, v115 quad_perm:[1,0,3,2] row_mask:0xf bank_mask:0xf
	s_nop 0
	v_cndmask_b32_e64 v160, v120, v116, s[40:41]
	v_cndmask_b32_e64 v161, v121, v117, s[40:41]
	v_cndmask_b32_e64 v162, v116, v122, s[40:41]
	v_cndmask_b32_e64 v163, v117, v123, s[40:41]
	v_cndmask_b32_e64 v164, v124, v118, s[40:41]
	v_cndmask_b32_e64 v165, v125, v119, s[40:41]
	v_cndmask_b32_e64 v166, v118, v126, s[40:41]
	v_cndmask_b32_e64 v167, v119, v127, s[40:41]
	global_store_dwordx4 v[132:133], v[160:163], off sc1
	global_store_dwordx4 v[132:133], v[164:167], off offset:1024 sc1
	v_lshl_add_u64 v[132:133], v[132:133], 0, v[154:155]
	global_load_dwordx4 v[0:3], v[128:129], off nt
	global_load_dwordx4 v[4:7], v[128:129], off offset:1024 nt
	global_load_dwordx4 v[8:11], v[128:129], off offset:2048 nt
	global_load_dwordx4 v[12:15], v[128:129], off offset:3072 nt
	v_lshl_add_u64 v[128:129], v[128:129], 0, v[152:153]
	v_add_f32_e32 v112, v16, v17
	v_add_f32_e32 v113, v18, v19
	v_add_f32_e32 v114, v20, v21
	v_add_f32_e32 v115, v22, v23
	v_add_f32_e32 v116, v24, v25
	v_add_f32_e32 v117, v26, v27
	v_add_f32_e32 v118, v28, v29
	v_add_f32_e32 v119, v30, v31
	v_add_f32_e32 v112, v112, v116
	v_add_f32_e32 v113, v113, v117
	v_add_f32_e32 v114, v114, v118
	v_add_f32_e32 v115, v115, v119
	v_add_f32_e32 v112, v112, v113
	v_add_f32_e32 v114, v114, v115
	v_add_f32_e32 v112, v112, v114
	s_nop 1
	v_add_f32_dpp v112, v112, v112 quad_perm:[1,0,3,2] row_mask:0xf bank_mask:0xf
	s_nop 1
	v_add_f32_dpp v112, v112, v112 quad_perm:[2,3,0,1] row_mask:0xf bank_mask:0xf
	s_nop 1
	v_add_f32_dpp v112, v112, v112 row_half_mirror row_mask:0xf bank_mask:0xf
	s_nop 1
	v_add_f32_dpp v112, v112, v112 row_mirror row_mask:0xf bank_mask:0xf
	s_nop 1
	v_add_f32_dpp v112, v112, v112 row_bcast:15 row_mask:0xa bank_mask:0xf
	s_nop 1
	v_add_f32_dpp v112, v112, v112 row_bcast:31 row_mask:0xc bank_mask:0xf
	s_nop 1
	v_readlane_b32 s2, v112, 63
	s_nop 1
	v_fmac_f32_e32 v16, s2, v142
	v_fmac_f32_e32 v17, s2, v142
	v_fmac_f32_e32 v18, s2, v142
	v_fmac_f32_e32 v19, s2, v142
	v_fmac_f32_e32 v20, s2, v142
	v_fmac_f32_e32 v21, s2, v142
	v_fmac_f32_e32 v22, s2, v142
	v_fmac_f32_e32 v23, s2, v142
	v_fmac_f32_e32 v24, s2, v142
	v_fmac_f32_e32 v25, s2, v142
	v_fmac_f32_e32 v26, s2, v142
	v_fmac_f32_e32 v27, s2, v142
	v_fmac_f32_e32 v28, s2, v142
	v_fmac_f32_e32 v29, s2, v142
	v_fmac_f32_e32 v30, s2, v142
	v_fmac_f32_e32 v31, s2, v142
	v_mul_f32_e32 v112, v16, v16
	v_mul_f32_e32 v113, v17, v17
	v_mul_f32_e32 v114, v18, v18
	v_mul_f32_e32 v115, v19, v19
	v_fmac_f32_e32 v112, v20, v20
	v_fmac_f32_e32 v113, v21, v21
	v_fmac_f32_e32 v114, v22, v22
	v_fmac_f32_e32 v115, v23, v23
	v_fmac_f32_e32 v112, v24, v24
	v_fmac_f32_e32 v113, v25, v25
	v_fmac_f32_e32 v114, v26, v26
	v_fmac_f32_e32 v115, v27, v27
	v_fmac_f32_e32 v112, v28, v28
	v_fmac_f32_e32 v113, v29, v29
	v_fmac_f32_e32 v114, v30, v30
	v_fmac_f32_e32 v115, v31, v31
	v_add_f32_e32 v112, v112, v113
	v_add_f32_e32 v114, v114, v115
	v_add_f32_e32 v112, v112, v114
	s_nop 1
	v_add_f32_dpp v112, v112, v112 quad_perm:[1,0,3,2] row_mask:0xf bank_mask:0xf
	s_nop 1
	v_add_f32_dpp v112, v112, v112 quad_perm:[2,3,0,1] row_mask:0xf bank_mask:0xf
	s_nop 1
	v_add_f32_dpp v112, v112, v112 row_half_mirror row_mask:0xf bank_mask:0xf
	s_nop 1
	v_add_f32_dpp v112, v112, v112 row_mirror row_mask:0xf bank_mask:0xf
	s_nop 1
	v_add_f32_dpp v112, v112, v112 row_bcast:15 row_mask:0xa bank_mask:0xf
	s_nop 1
	v_add_f32_dpp v112, v112, v112 row_bcast:31 row_mask:0xc bank_mask:0xf
	s_nop 1
	v_readlane_b32 s2, v112, 63
	s_nop 1
	v_mov_b32_e32 v113, 0x358637bd
	v_mov_b32_e32 v114, 0x3a800000
	v_fmac_f32_e32 v113, s2, v114
	v_rsq_f32_e32 v115, v113
	v_mul_f32_e32 v113, 0.5, v113
	v_mul_f32_e32 v116, v115, v115
	v_mov_b32_e32 v117, 0x3fc00000
	v_fma_f32 v116, -v113, v116, v117
	v_mul_f32_e32 v144, v115, v116
	v_pk_mul_f32 v[16:17], v[16:17], v[144:145] op_sel_hi:[1,0]
	v_pk_mul_f32 v[18:19], v[18:19], v[144:145] op_sel_hi:[1,0]
	v_pk_mul_f32 v[20:21], v[20:21], v[144:145] op_sel_hi:[1,0]
	v_pk_mul_f32 v[22:23], v[22:23], v[144:145] op_sel_hi:[1,0]
	v_pk_mul_f32 v[24:25], v[24:25], v[144:145] op_sel_hi:[1,0]
	v_pk_mul_f32 v[26:27], v[26:27], v[144:145] op_sel_hi:[1,0]
	v_pk_mul_f32 v[28:29], v[28:29], v[144:145] op_sel_hi:[1,0]
	v_pk_mul_f32 v[30:31], v[30:31], v[144:145] op_sel_hi:[1,0]
	v_pk_fma_f32 v[16:17], v[64:65], v[16:17], v[48:49]
	v_pk_fma_f32 v[18:19], v[66:67], v[18:19], v[50:51]
	v_pk_fma_f32 v[20:21], v[68:69], v[20:21], v[52:53]
	v_pk_fma_f32 v[22:23], v[70:71], v[22:23], v[54:55]
	v_pk_fma_f32 v[24:25], v[72:73], v[24:25], v[56:57]
	v_pk_fma_f32 v[26:27], v[74:75], v[26:27], v[58:59]
	v_pk_fma_f32 v[28:29], v[76:77], v[28:29], v[60:61]
	v_pk_fma_f32 v[30:31], v[78:79], v[30:31], v[62:63]
	v_cvt_pk_bf16_f32 v120, v16, v17
	v_cvt_pk_bf16_f32 v121, v18, v19
	v_cvt_pk_bf16_f32 v122, v20, v21
	v_cvt_pk_bf16_f32 v123, v22, v23
	v_cvt_pk_bf16_f32 v124, v24, v25
	v_cvt_pk_bf16_f32 v125, v26, v27
	v_cvt_pk_bf16_f32 v126, v28, v29
	v_cvt_pk_bf16_f32 v127, v30, v31
	v_cndmask_b32_e64 v112, v122, v120, s[40:41]
	v_cndmask_b32_e64 v113, v123, v121, s[40:41]
	v_cndmask_b32_e64 v114, v126, v124, s[40:41]
	v_cndmask_b32_e64 v115, v127, v125, s[40:41]
	v_mov_b32_dpp v116, v112 quad_perm:[1,0,3,2] row_mask:0xf bank_mask:0xf
	v_mov_b32_dpp v117, v113 quad_perm:[1,0,3,2] row_mask:0xf bank_mask:0xf
	v_mov_b32_dpp v118, v114 quad_perm:[1,0,3,2] row_mask:0xf bank_mask:0xf
	v_mov_b32_dpp v119, v115 quad_perm:[1,0,3,2] row_mask:0xf bank_mask:0xf
	s_nop 0
	v_cndmask_b32_e64 v160, v120, v116, s[40:41]
	v_cndmask_b32_e64 v161, v121, v117, s[40:41]
	v_cndmask_b32_e64 v162, v116, v122, s[40:41]
	v_cndmask_b32_e64 v163, v117, v123, s[40:41]
	v_cndmask_b32_e64 v164, v124, v118, s[40:41]
	v_cndmask_b32_e64 v165, v125, v119, s[40:41]
	v_cndmask_b32_e64 v166, v118, v126, s[40:41]
	v_cndmask_b32_e64 v167, v119, v127, s[40:41]
	global_store_dwordx4 v[132:133], v[160:163], off sc1
	global_store_dwordx4 v[132:133], v[164:167], off offset:1024 sc1
	v_lshl_add_u64 v[132:133], v[132:133], 0, v[154:155]
	global_load_dwordx4 v[48:51], v[134:135], off offset:-4096
	global_load_dwordx4 v[52:55], v[134:135], off offset:-3072
	global_load_dwordx4 v[56:59], v[134:135], off offset:-2048
	global_load_dwordx4 v[60:63], v[134:135], off offset:-1024
	global_load_dwordx4 v[64:67], v[134:135], off
	global_load_dwordx4 v[68:71], v[134:135], off offset:1024
	global_load_dwordx4 v[72:75], v[134:135], off offset:2048
	global_load_dwordx4 v[76:79], v[134:135], off offset:3072
	v_lshl_add_u64 v[134:135], v[134:135], 0, v[156:157]
	global_load_dwordx4 v[16:19], v[128:129], off nt
	global_load_dwordx4 v[20:23], v[128:129], off offset:1024 nt
	global_load_dwordx4 v[24:27], v[128:129], off offset:2048 nt
	global_load_dwordx4 v[28:31], v[128:129], off offset:3072 nt
	v_lshl_add_u64 v[128:129], v[128:129], 0, v[152:153]
	s_waitcnt vmcnt(20)
	v_add_f32_e32 v112, v32, v33
	v_add_f32_e32 v113, v34, v35
	v_add_f32_e32 v114, v36, v37
	v_add_f32_e32 v115, v38, v39
	v_add_f32_e32 v116, v40, v41
	v_add_f32_e32 v117, v42, v43
	v_add_f32_e32 v118, v44, v45
	v_add_f32_e32 v119, v46, v47
	v_add_f32_e32 v112, v112, v116
	v_add_f32_e32 v113, v113, v117
	v_add_f32_e32 v114, v114, v118
	v_add_f32_e32 v115, v115, v119
	v_add_f32_e32 v112, v112, v113
	v_add_f32_e32 v114, v114, v115
	v_add_f32_e32 v112, v112, v114
	s_nop 1
	v_add_f32_dpp v112, v112, v112 quad_perm:[1,0,3,2] row_mask:0xf bank_mask:0xf
	s_nop 1
	v_add_f32_dpp v112, v112, v112 quad_perm:[2,3,0,1] row_mask:0xf bank_mask:0xf
	s_nop 1
	v_add_f32_dpp v112, v112, v112 row_half_mirror row_mask:0xf bank_mask:0xf
	s_nop 1
	v_add_f32_dpp v112, v112, v112 row_mirror row_mask:0xf bank_mask:0xf
	s_nop 1
	v_add_f32_dpp v112, v112, v112 row_bcast:15 row_mask:0xa bank_mask:0xf
	s_nop 1
	v_add_f32_dpp v112, v112, v112 row_bcast:31 row_mask:0xc bank_mask:0xf
	s_nop 1
	v_readlane_b32 s2, v112, 63
	s_nop 1
	v_fmac_f32_e32 v32, s2, v142
	v_fmac_f32_e32 v33, s2, v142
	v_fmac_f32_e32 v34, s2, v142
	v_fmac_f32_e32 v35, s2, v142
	v_fmac_f32_e32 v36, s2, v142
	v_fmac_f32_e32 v37, s2, v142
	v_fmac_f32_e32 v38, s2, v142
	v_fmac_f32_e32 v39, s2, v142
	v_fmac_f32_e32 v40, s2, v142
	v_fmac_f32_e32 v41, s2, v142
	v_fmac_f32_e32 v42, s2, v142
	v_fmac_f32_e32 v43, s2, v142
	v_fmac_f32_e32 v44, s2, v142
	v_fmac_f32_e32 v45, s2, v142
	v_fmac_f32_e32 v46, s2, v142
	v_fmac_f32_e32 v47, s2, v142
	v_mul_f32_e32 v112, v32, v32
	v_mul_f32_e32 v113, v33, v33
	v_mul_f32_e32 v114, v34, v34
	v_mul_f32_e32 v115, v35, v35
	v_fmac_f32_e32 v112, v36, v36
	v_fmac_f32_e32 v113, v37, v37
	v_fmac_f32_e32 v114, v38, v38
	v_fmac_f32_e32 v115, v39, v39
	v_fmac_f32_e32 v112, v40, v40
	v_fmac_f32_e32 v113, v41, v41
	v_fmac_f32_e32 v114, v42, v42
	v_fmac_f32_e32 v115, v43, v43
	v_fmac_f32_e32 v112, v44, v44
	v_fmac_f32_e32 v113, v45, v45
	v_fmac_f32_e32 v114, v46, v46
	v_fmac_f32_e32 v115, v47, v47
	v_add_f32_e32 v112, v112, v113
	v_add_f32_e32 v114, v114, v115
	v_add_f32_e32 v112, v112, v114
	s_nop 1
	v_add_f32_dpp v112, v112, v112 quad_perm:[1,0,3,2] row_mask:0xf bank_mask:0xf
	s_nop 1
	v_add_f32_dpp v112, v112, v112 quad_perm:[2,3,0,1] row_mask:0xf bank_mask:0xf
	s_nop 1
	v_add_f32_dpp v112, v112, v112 row_half_mirror row_mask:0xf bank_mask:0xf
	s_nop 1
	v_add_f32_dpp v112, v112, v112 row_mirror row_mask:0xf bank_mask:0xf
	s_nop 1
	v_add_f32_dpp v112, v112, v112 row_bcast:15 row_mask:0xa bank_mask:0xf
	s_nop 1
	v_add_f32_dpp v112, v112, v112 row_bcast:31 row_mask:0xc bank_mask:0xf
	s_nop 1
	v_readlane_b32 s2, v112, 63
	s_nop 1
	v_mov_b32_e32 v113, 0x358637bd
	v_mov_b32_e32 v114, 0x3a800000
	v_fmac_f32_e32 v113, s2, v114
	v_rsq_f32_e32 v115, v113
	v_mul_f32_e32 v113, 0.5, v113
	v_mul_f32_e32 v116, v115, v115
	v_mov_b32_e32 v117, 0x3fc00000
	v_fma_f32 v116, -v113, v116, v117
	v_mul_f32_e32 v144, v115, v116
	v_pk_mul_f32 v[32:33], v[32:33], v[144:145] op_sel_hi:[1,0]
	v_pk_mul_f32 v[34:35], v[34:35], v[144:145] op_sel_hi:[1,0]
	v_pk_mul_f32 v[36:37], v[36:37], v[144:145] op_sel_hi:[1,0]
	v_pk_mul_f32 v[38:39], v[38:39], v[144:145] op_sel_hi:[1,0]
	v_pk_mul_f32 v[40:41], v[40:41], v[144:145] op_sel_hi:[1,0]
	v_pk_mul_f32 v[42:43], v[42:43], v[144:145] op_sel_hi:[1,0]
	v_pk_mul_f32 v[44:45], v[44:45], v[144:145] op_sel_hi:[1,0]
	v_pk_mul_f32 v[46:47], v[46:47], v[144:145] op_sel_hi:[1,0]
	s_waitcnt vmcnt(4)
	v_pk_add_f32 v[64:65], v[64:65], 1.0 op_sel_hi:[1,0]
	v_pk_add_f32 v[66:67], v[66:67], 1.0 op_sel_hi:[1,0]
	v_pk_add_f32 v[68:69], v[68:69], 1.0 op_sel_hi:[1,0]
	v_pk_add_f32 v[70:71], v[70:71], 1.0 op_sel_hi:[1,0]
	v_pk_add_f32 v[72:73], v[72:73], 1.0 op_sel_hi:[1,0]
	v_pk_add_f32 v[74:75], v[74:75], 1.0 op_sel_hi:[1,0]
	v_pk_add_f32 v[76:77], v[76:77], 1.0 op_sel_hi:[1,0]
	v_pk_add_f32 v[78:79], v[78:79], 1.0 op_sel_hi:[1,0]
	v_pk_fma_f32 v[32:33], v[64:65], v[32:33], v[48:49]
	v_pk_fma_f32 v[34:35], v[66:67], v[34:35], v[50:51]
	v_pk_fma_f32 v[36:37], v[68:69], v[36:37], v[52:53]
	v_pk_fma_f32 v[38:39], v[70:71], v[38:39], v[54:55]
	v_pk_fma_f32 v[40:41], v[72:73], v[40:41], v[56:57]
	v_pk_fma_f32 v[42:43], v[74:75], v[42:43], v[58:59]
	v_pk_fma_f32 v[44:45], v[76:77], v[44:45], v[60:61]
	v_pk_fma_f32 v[46:47], v[78:79], v[46:47], v[62:63]
	v_cvt_pk_bf16_f32 v120, v32, v33
	v_cvt_pk_bf16_f32 v121, v34, v35
	v_cvt_pk_bf16_f32 v122, v36, v37
	v_cvt_pk_bf16_f32 v123, v38, v39
	v_cvt_pk_bf16_f32 v124, v40, v41
	v_cvt_pk_bf16_f32 v125, v42, v43
	v_cvt_pk_bf16_f32 v126, v44, v45
	v_cvt_pk_bf16_f32 v127, v46, v47
	v_cndmask_b32_e64 v112, v122, v120, s[40:41]
	v_cndmask_b32_e64 v113, v123, v121, s[40:41]
	v_cndmask_b32_e64 v114, v126, v124, s[40:41]
	v_cndmask_b32_e64 v115, v127, v125, s[40:41]
	v_mov_b32_dpp v116, v112 quad_perm:[1,0,3,2] row_mask:0xf bank_mask:0xf
	v_mov_b32_dpp v117, v113 quad_perm:[1,0,3,2] row_mask:0xf bank_mask:0xf
	v_mov_b32_dpp v118, v114 quad_perm:[1,0,3,2] row_mask:0xf bank_mask:0xf
	v_mov_b32_dpp v119, v115 quad_perm:[1,0,3,2] row_mask:0xf bank_mask:0xf
	s_nop 0
	v_cndmask_b32_e64 v160, v120, v116, s[40:41]
	v_cndmask_b32_e64 v161, v121, v117, s[40:41]
	v_cndmask_b32_e64 v162, v116, v122, s[40:41]
	v_cndmask_b32_e64 v163, v117, v123, s[40:41]
	v_cndmask_b32_e64 v164, v124, v118, s[40:41]
	v_cndmask_b32_e64 v165, v125, v119, s[40:41]
	v_cndmask_b32_e64 v166, v118, v126, s[40:41]
	v_cndmask_b32_e64 v167, v119, v127, s[40:41]
	global_store_dwordx4 v[132:133], v[160:163], off sc1
	global_store_dwordx4 v[132:133], v[164:167], off offset:1024 sc1
	v_lshl_add_u64 v[132:133], v[132:133], 0, v[154:155]
	global_load_dwordx4 v[32:35], v[128:129], off nt
	global_load_dwordx4 v[36:39], v[128:129], off offset:1024 nt
	global_load_dwordx4 v[40:43], v[128:129], off offset:2048 nt
	global_load_dwordx4 v[44:47], v[128:129], off offset:3072 nt
	v_lshl_add_u64 v[128:129], v[128:129], 0, v[152:153]
	s_cmp_lg_u32 s0, 2
	s_cbranch_scc1 .Lln0_nopark
	v_lshl_add_u64 v[128:129], s[60:61], 0, v[148:149]
.Lln0_nopark:
	v_add_f32_e32 v112, v0, v1
	v_add_f32_e32 v113, v2, v3
	v_add_f32_e32 v114, v4, v5
	v_add_f32_e32 v115, v6, v7
	v_add_f32_e32 v116, v8, v9
	v_add_f32_e32 v117, v10, v11
	v_add_f32_e32 v118, v12, v13
	v_add_f32_e32 v119, v14, v15
	v_add_f32_e32 v112, v112, v116
	v_add_f32_e32 v113, v113, v117
	v_add_f32_e32 v114, v114, v118
	v_add_f32_e32 v115, v115, v119
	v_add_f32_e32 v112, v112, v113
	v_add_f32_e32 v114, v114, v115
	v_add_f32_e32 v112, v112, v114
	s_nop 1
	v_add_f32_dpp v112, v112, v112 quad_perm:[1,0,3,2] row_mask:0xf bank_mask:0xf
	s_nop 1
	v_add_f32_dpp v112, v112, v112 quad_perm:[2,3,0,1] row_mask:0xf bank_mask:0xf
	s_nop 1
	v_add_f32_dpp v112, v112, v112 row_half_mirror row_mask:0xf bank_mask:0xf
	s_nop 1
	v_add_f32_dpp v112, v112, v112 row_mirror row_mask:0xf bank_mask:0xf
	s_nop 1
	v_add_f32_dpp v112, v112, v112 row_bcast:15 row_mask:0xa bank_mask:0xf
	s_nop 1
	v_add_f32_dpp v112, v112, v112 row_bcast:31 row_mask:0xc bank_mask:0xf
	s_nop 1
	v_readlane_b32 s2, v112, 63
	s_nop 1
	v_fmac_f32_e32 v0, s2, v142
	v_fmac_f32_e32 v1, s2, v142
	v_fmac_f32_e32 v2, s2, v142
	v_fmac_f32_e32 v3, s2, v142
	v_fmac_f32_e32 v4, s2, v142
	v_fmac_f32_e32 v5, s2, v142
	v_fmac_f32_e32 v6, s2, v142
	v_fmac_f32_e32 v7, s2, v142
	v_fmac_f32_e32 v8, s2, v142
	v_fmac_f32_e32 v9, s2, v142
	v_fmac_f32_e32 v10, s2, v142
	v_fmac_f32_e32 v11, s2, v142
	v_fmac_f32_e32 v12, s2, v142
	v_fmac_f32_e32 v13, s2, v142
	v_fmac_f32_e32 v14, s2, v142
	v_fmac_f32_e32 v15, s2, v142
	v_mul_f32_e32 v112, v0, v0
	v_mul_f32_e32 v113, v1, v1
	v_mul_f32_e32 v114, v2, v2
	v_mul_f32_e32 v115, v3, v3
	v_fmac_f32_e32 v112, v4, v4
	v_fmac_f32_e32 v113, v5, v5
	v_fmac_f32_e32 v114, v6, v6
	v_fmac_f32_e32 v115, v7, v7
	v_fmac_f32_e32 v112, v8, v8
	v_fmac_f32_e32 v113, v9, v9
	v_fmac_f32_e32 v114, v10, v10
	v_fmac_f32_e32 v115, v11, v11
	v_fmac_f32_e32 v112, v12, v12
	v_fmac_f32_e32 v113, v13, v13
	v_fmac_f32_e32 v114, v14, v14
	v_fmac_f32_e32 v115, v15, v15
	v_add_f32_e32 v112, v112, v113
	v_add_f32_e32 v114, v114, v115
	v_add_f32_e32 v112, v112, v114
	s_nop 1
	v_add_f32_dpp v112, v112, v112 quad_perm:[1,0,3,2] row_mask:0xf bank_mask:0xf
	s_nop 1
	v_add_f32_dpp v112, v112, v112 quad_perm:[2,3,0,1] row_mask:0xf bank_mask:0xf
	s_nop 1
	v_add_f32_dpp v112, v112, v112 row_half_mirror row_mask:0xf bank_mask:0xf
	s_nop 1
	v_add_f32_dpp v112, v112, v112 row_mirror row_mask:0xf bank_mask:0xf
	s_nop 1
	v_add_f32_dpp v112, v112, v112 row_bcast:15 row_mask:0xa bank_mask:0xf
	s_nop 1
	v_add_f32_dpp v112, v112, v112 row_bcast:31 row_mask:0xc bank_mask:0xf
	s_nop 1
	v_readlane_b32 s2, v112, 63
	s_nop 1
	v_mov_b32_e32 v113, 0x358637bd
	v_mov_b32_e32 v114, 0x3a800000
	v_fmac_f32_e32 v113, s2, v114
	v_rsq_f32_e32 v115, v113
	v_mul_f32_e32 v113, 0.5, v113
	v_mul_f32_e32 v116, v115, v115
	v_mov_b32_e32 v117, 0x3fc00000
	v_fma_f32 v116, -v113, v116, v117
	v_mul_f32_e32 v144, v115, v116
	v_pk_mul_f32 v[0:1], v[0:1], v[144:145] op_sel_hi:[1,0]
	v_pk_mul_f32 v[2:3], v[2:3], v[144:145] op_sel_hi:[1,0]
	v_pk_mul_f32 v[4:5], v[4:5], v[144:145] op_sel_hi:[1,0]
	v_pk_mul_f32 v[6:7], v[6:7], v[144:145] op_sel_hi:[1,0]
	v_pk_mul_f32 v[8:9], v[8:9], v[144:145] op_sel_hi:[1,0]
	v_pk_mul_f32 v[10:11], v[10:11], v[144:145] op_sel_hi:[1,0]
	v_pk_mul_f32 v[12:13], v[12:13], v[144:145] op_sel_hi:[1,0]
	v_pk_mul_f32 v[14:15], v[14:15], v[144:145] op_sel_hi:[1,0]
	v_pk_fma_f32 v[0:1], v[64:65], v[0:1], v[48:49]
	v_pk_fma_f32 v[2:3], v[66:67], v[2:3], v[50:51]
	v_pk_fma_f32 v[4:5], v[68:69], v[4:5], v[52:53]
	v_pk_fma_f32 v[6:7], v[70:71], v[6:7], v[54:55]
	v_pk_fma_f32 v[8:9], v[72:73], v[8:9], v[56:57]
	v_pk_fma_f32 v[10:11], v[74:75], v[10:11], v[58:59]
	v_pk_fma_f32 v[12:13], v[76:77], v[12:13], v[60:61]
	v_pk_fma_f32 v[14:15], v[78:79], v[14:15], v[62:63]
	v_cvt_pk_bf16_f32 v120, v0, v1
	v_cvt_pk_bf16_f32 v121, v2, v3
	v_cvt_pk_bf16_f32 v122, v4, v5
	v_cvt_pk_bf16_f32 v123, v6, v7
	v_cvt_pk_bf16_f32 v124, v8, v9
	v_cvt_pk_bf16_f32 v125, v10, v11
	v_cvt_pk_bf16_f32 v126, v12, v13
	v_cvt_pk_bf16_f32 v127, v14, v15
	v_cndmask_b32_e64 v112, v122, v120, s[40:41]
	v_cndmask_b32_e64 v113, v123, v121, s[40:41]
	v_cndmask_b32_e64 v114, v126, v124, s[40:41]
	v_cndmask_b32_e64 v115, v127, v125, s[40:41]
	v_mov_b32_dpp v116, v112 quad_perm:[1,0,3,2] row_mask:0xf bank_mask:0xf
	v_mov_b32_dpp v117, v113 quad_perm:[1,0,3,2] row_mask:0xf bank_mask:0xf
	v_mov_b32_dpp v118, v114 quad_perm:[1,0,3,2] row_mask:0xf bank_mask:0xf
	v_mov_b32_dpp v119, v115 quad_perm:[1,0,3,2] row_mask:0xf bank_mask:0xf
	s_nop 0
	v_cndmask_b32_e64 v160, v120, v116, s[40:41]
	v_cndmask_b32_e64 v161, v121, v117, s[40:41]
	v_cndmask_b32_e64 v162, v116, v122, s[40:41]
	v_cndmask_b32_e64 v163, v117, v123, s[40:41]
	v_cndmask_b32_e64 v164, v124, v118, s[40:41]
	v_cndmask_b32_e64 v165, v125, v119, s[40:41]
	v_cndmask_b32_e64 v166, v118, v126, s[40:41]
	v_cndmask_b32_e64 v167, v119, v127, s[40:41]
	global_store_dwordx4 v[132:133], v[160:163], off sc1
	global_store_dwordx4 v[132:133], v[164:167], off offset:1024 sc1
	v_lshl_add_u64 v[132:133], v[132:133], 0, v[154:155]
	global_load_dwordx4 v[48:51], v[134:135], off offset:-4096
	global_load_dwordx4 v[52:55], v[134:135], off offset:-3072
	global_load_dwordx4 v[56:59], v[134:135], off offset:-2048
	global_load_dwordx4 v[60:63], v[134:135], off offset:-1024
	global_load_dwordx4 v[64:67], v[134:135], off
	global_load_dwordx4 v[68:71], v[134:135], off offset:1024
	global_load_dwordx4 v[72:75], v[134:135], off offset:2048
	global_load_dwordx4 v[76:79], v[134:135], off offset:3072
	v_lshl_add_u64 v[134:135], v[134:135], 0, v[156:157]
	global_load_dwordx4 v[0:3], v[128:129], off nt
	global_load_dwordx4 v[4:7], v[128:129], off offset:1024 nt
	global_load_dwordx4 v[8:11], v[128:129], off offset:2048 nt
	global_load_dwordx4 v[12:15], v[128:129], off offset:3072 nt
	v_lshl_add_u64 v[128:129], v[128:129], 0, v[152:153]
	s_waitcnt vmcnt(20)
	v_add_f32_e32 v112, v16, v17
	v_add_f32_e32 v113, v18, v19
	v_add_f32_e32 v114, v20, v21
	v_add_f32_e32 v115, v22, v23
	v_add_f32_e32 v116, v24, v25
	v_add_f32_e32 v117, v26, v27
	v_add_f32_e32 v118, v28, v29
	v_add_f32_e32 v119, v30, v31
	v_add_f32_e32 v112, v112, v116
	v_add_f32_e32 v113, v113, v117
	v_add_f32_e32 v114, v114, v118
	v_add_f32_e32 v115, v115, v119
	v_add_f32_e32 v112, v112, v113
	v_add_f32_e32 v114, v114, v115
	v_add_f32_e32 v112, v112, v114
	s_nop 1
	v_add_f32_dpp v112, v112, v112 quad_perm:[1,0,3,2] row_mask:0xf bank_mask:0xf
	s_nop 1
	v_add_f32_dpp v112, v112, v112 quad_perm:[2,3,0,1] row_mask:0xf bank_mask:0xf
	s_nop 1
	v_add_f32_dpp v112, v112, v112 row_half_mirror row_mask:0xf bank_mask:0xf
	s_nop 1
	v_add_f32_dpp v112, v112, v112 row_mirror row_mask:0xf bank_mask:0xf
	s_nop 1
	v_add_f32_dpp v112, v112, v112 row_bcast:15 row_mask:0xa bank_mask:0xf
	s_nop 1
	v_add_f32_dpp v112, v112, v112 row_bcast:31 row_mask:0xc bank_mask:0xf
	s_nop 1
	v_readlane_b32 s2, v112, 63
	s_nop 1
	v_fmac_f32_e32 v16, s2, v142
	v_fmac_f32_e32 v17, s2, v142
	v_fmac_f32_e32 v18, s2, v142
	v_fmac_f32_e32 v19, s2, v142
	v_fmac_f32_e32 v20, s2, v142
	v_fmac_f32_e32 v21, s2, v142
	v_fmac_f32_e32 v22, s2, v142
	v_fmac_f32_e32 v23, s2, v142
	v_fmac_f32_e32 v24, s2, v142
	v_fmac_f32_e32 v25, s2, v142
	v_fmac_f32_e32 v26, s2, v142
	v_fmac_f32_e32 v27, s2, v142
	v_fmac_f32_e32 v28, s2, v142
	v_fmac_f32_e32 v29, s2, v142
	v_fmac_f32_e32 v30, s2, v142
	v_fmac_f32_e32 v31, s2, v142
	v_mul_f32_e32 v112, v16, v16
	v_mul_f32_e32 v113, v17, v17
	v_mul_f32_e32 v114, v18, v18
	v_mul_f32_e32 v115, v19, v19
	v_fmac_f32_e32 v112, v20, v20
	v_fmac_f32_e32 v113, v21, v21
	v_fmac_f32_e32 v114, v22, v22
	v_fmac_f32_e32 v115, v23, v23
	v_fmac_f32_e32 v112, v24, v24
	v_fmac_f32_e32 v113, v25, v25
	v_fmac_f32_e32 v114, v26, v26
	v_fmac_f32_e32 v115, v27, v27
	v_fmac_f32_e32 v112, v28, v28
	v_fmac_f32_e32 v113, v29, v29
	v_fmac_f32_e32 v114, v30, v30
	v_fmac_f32_e32 v115, v31, v31
	v_add_f32_e32 v112, v112, v113
	v_add_f32_e32 v114, v114, v115
	v_add_f32_e32 v112, v112, v114
	s_nop 1
	v_add_f32_dpp v112, v112, v112 quad_perm:[1,0,3,2] row_mask:0xf bank_mask:0xf
	s_nop 1
	v_add_f32_dpp v112, v112, v112 quad_perm:[2,3,0,1] row_mask:0xf bank_mask:0xf
	s_nop 1
	v_add_f32_dpp v112, v112, v112 row_half_mirror row_mask:0xf bank_mask:0xf
	s_nop 1
	v_add_f32_dpp v112, v112, v112 row_mirror row_mask:0xf bank_mask:0xf
	s_nop 1
	v_add_f32_dpp v112, v112, v112 row_bcast:15 row_mask:0xa bank_mask:0xf
	s_nop 1
	v_add_f32_dpp v112, v112, v112 row_bcast:31 row_mask:0xc bank_mask:0xf
	s_nop 1
	v_readlane_b32 s2, v112, 63
	s_nop 1
	v_mov_b32_e32 v113, 0x358637bd
	v_mov_b32_e32 v114, 0x3a800000
	v_fmac_f32_e32 v113, s2, v114
	v_rsq_f32_e32 v115, v113
	v_mul_f32_e32 v113, 0.5, v113
	v_mul_f32_e32 v116, v115, v115
	v_mov_b32_e32 v117, 0x3fc00000
	v_fma_f32 v116, -v113, v116, v117
	v_mul_f32_e32 v144, v115, v116
	v_pk_mul_f32 v[16:17], v[16:17], v[144:145] op_sel_hi:[1,0]
	v_pk_mul_f32 v[18:19], v[18:19], v[144:145] op_sel_hi:[1,0]
	v_pk_mul_f32 v[20:21], v[20:21], v[144:145] op_sel_hi:[1,0]
	v_pk_mul_f32 v[22:23], v[22:23], v[144:145] op_sel_hi:[1,0]
	v_pk_mul_f32 v[24:25], v[24:25], v[144:145] op_sel_hi:[1,0]
	v_pk_mul_f32 v[26:27], v[26:27], v[144:145] op_sel_hi:[1,0]
	v_pk_mul_f32 v[28:29], v[28:29], v[144:145] op_sel_hi:[1,0]
	v_pk_mul_f32 v[30:31], v[30:31], v[144:145] op_sel_hi:[1,0]
	s_waitcnt vmcnt(4)
	v_pk_add_f32 v[64:65], v[64:65], 1.0 op_sel_hi:[1,0]
	v_pk_add_f32 v[66:67], v[66:67], 1.0 op_sel_hi:[1,0]
	v_pk_add_f32 v[68:69], v[68:69], 1.0 op_sel_hi:[1,0]
	v_pk_add_f32 v[70:71], v[70:71], 1.0 op_sel_hi:[1,0]
	v_pk_add_f32 v[72:73], v[72:73], 1.0 op_sel_hi:[1,0]
	v_pk_add_f32 v[74:75], v[74:75], 1.0 op_sel_hi:[1,0]
	v_pk_add_f32 v[76:77], v[76:77], 1.0 op_sel_hi:[1,0]
	v_pk_add_f32 v[78:79], v[78:79], 1.0 op_sel_hi:[1,0]
	v_pk_fma_f32 v[16:17], v[64:65], v[16:17], v[48:49]
	v_pk_fma_f32 v[18:19], v[66:67], v[18:19], v[50:51]
	v_pk_fma_f32 v[20:21], v[68:69], v[20:21], v[52:53]
	v_pk_fma_f32 v[22:23], v[70:71], v[22:23], v[54:55]
	v_pk_fma_f32 v[24:25], v[72:73], v[24:25], v[56:57]
	v_pk_fma_f32 v[26:27], v[74:75], v[26:27], v[58:59]
	v_pk_fma_f32 v[28:29], v[76:77], v[28:29], v[60:61]
	v_pk_fma_f32 v[30:31], v[78:79], v[30:31], v[62:63]
	v_cvt_pk_bf16_f32 v120, v16, v17
	v_cvt_pk_bf16_f32 v121, v18, v19
	v_cvt_pk_bf16_f32 v122, v20, v21
	v_cvt_pk_bf16_f32 v123, v22, v23
	v_cvt_pk_bf16_f32 v124, v24, v25
	v_cvt_pk_bf16_f32 v125, v26, v27
	v_cvt_pk_bf16_f32 v126, v28, v29
	v_cvt_pk_bf16_f32 v127, v30, v31
	v_cndmask_b32_e64 v112, v122, v120, s[40:41]
	v_cndmask_b32_e64 v113, v123, v121, s[40:41]
	v_cndmask_b32_e64 v114, v126, v124, s[40:41]
	v_cndmask_b32_e64 v115, v127, v125, s[40:41]
	v_mov_b32_dpp v116, v112 quad_perm:[1,0,3,2] row_mask:0xf bank_mask:0xf
	v_mov_b32_dpp v117, v113 quad_perm:[1,0,3,2] row_mask:0xf bank_mask:0xf
	v_mov_b32_dpp v118, v114 quad_perm:[1,0,3,2] row_mask:0xf bank_mask:0xf
	v_mov_b32_dpp v119, v115 quad_perm:[1,0,3,2] row_mask:0xf bank_mask:0xf
	s_nop 0
	v_cndmask_b32_e64 v160, v120, v116, s[40:41]
	v_cndmask_b32_e64 v161, v121, v117, s[40:41]
	v_cndmask_b32_e64 v162, v116, v122, s[40:41]
	v_cndmask_b32_e64 v163, v117, v123, s[40:41]
	v_cndmask_b32_e64 v164, v124, v118, s[40:41]
	v_cndmask_b32_e64 v165, v125, v119, s[40:41]
	v_cndmask_b32_e64 v166, v118, v126, s[40:41]
	v_cndmask_b32_e64 v167, v119, v127, s[40:41]
	global_store_dwordx4 v[132:133], v[160:163], off sc1
	global_store_dwordx4 v[132:133], v[164:167], off offset:1024 sc1
	v_lshl_add_u64 v[132:133], v[132:133], 0, v[154:155]
	global_load_dwordx4 v[16:19], v[128:129], off nt
	global_load_dwordx4 v[20:23], v[128:129], off offset:1024 nt
	global_load_dwordx4 v[24:27], v[128:129], off offset:2048 nt
	global_load_dwordx4 v[28:31], v[128:129], off offset:3072 nt
	v_lshl_add_u64 v[128:129], v[128:129], 0, v[152:153]
	v_add_f32_e32 v112, v32, v33
	v_add_f32_e32 v113, v34, v35
	v_add_f32_e32 v114, v36, v37
	v_add_f32_e32 v115, v38, v39
	v_add_f32_e32 v116, v40, v41
	v_add_f32_e32 v117, v42, v43
	v_add_f32_e32 v118, v44, v45
	v_add_f32_e32 v119, v46, v47
	v_add_f32_e32 v112, v112, v116
	v_add_f32_e32 v113, v113, v117
	v_add_f32_e32 v114, v114, v118
	v_add_f32_e32 v115, v115, v119
	v_add_f32_e32 v112, v112, v113
	v_add_f32_e32 v114, v114, v115
	v_add_f32_e32 v112, v112, v114
	s_nop 1
	v_add_f32_dpp v112, v112, v112 quad_perm:[1,0,3,2] row_mask:0xf bank_mask:0xf
	s_nop 1
	v_add_f32_dpp v112, v112, v112 quad_perm:[2,3,0,1] row_mask:0xf bank_mask:0xf
	s_nop 1
	v_add_f32_dpp v112, v112, v112 row_half_mirror row_mask:0xf bank_mask:0xf
	s_nop 1
	v_add_f32_dpp v112, v112, v112 row_mirror row_mask:0xf bank_mask:0xf
	s_nop 1
	v_add_f32_dpp v112, v112, v112 row_bcast:15 row_mask:0xa bank_mask:0xf
	s_nop 1
	v_add_f32_dpp v112, v112, v112 row_bcast:31 row_mask:0xc bank_mask:0xf
	s_nop 1
	v_readlane_b32 s2, v112, 63
	s_nop 1
	v_fmac_f32_e32 v32, s2, v142
	v_fmac_f32_e32 v33, s2, v142
	v_fmac_f32_e32 v34, s2, v142
	v_fmac_f32_e32 v35, s2, v142
	v_fmac_f32_e32 v36, s2, v142
	v_fmac_f32_e32 v37, s2, v142
	v_fmac_f32_e32 v38, s2, v142
	v_fmac_f32_e32 v39, s2, v142
	v_fmac_f32_e32 v40, s2, v142
	v_fmac_f32_e32 v41, s2, v142
	v_fmac_f32_e32 v42, s2, v142
	v_fmac_f32_e32 v43, s2, v142
	v_fmac_f32_e32 v44, s2, v142
	v_fmac_f32_e32 v45, s2, v142
	v_fmac_f32_e32 v46, s2, v142
	v_fmac_f32_e32 v47, s2, v142
	v_mul_f32_e32 v112, v32, v32
	v_mul_f32_e32 v113, v33, v33
	v_mul_f32_e32 v114, v34, v34
	v_mul_f32_e32 v115, v35, v35
	v_fmac_f32_e32 v112, v36, v36
	v_fmac_f32_e32 v113, v37, v37
	v_fmac_f32_e32 v114, v38, v38
	v_fmac_f32_e32 v115, v39, v39
	v_fmac_f32_e32 v112, v40, v40
	v_fmac_f32_e32 v113, v41, v41
	v_fmac_f32_e32 v114, v42, v42
	v_fmac_f32_e32 v115, v43, v43
	v_fmac_f32_e32 v112, v44, v44
	v_fmac_f32_e32 v113, v45, v45
	v_fmac_f32_e32 v114, v46, v46
	v_fmac_f32_e32 v115, v47, v47
	v_add_f32_e32 v112, v112, v113
	v_add_f32_e32 v114, v114, v115
	v_add_f32_e32 v112, v112, v114
	s_nop 1
	v_add_f32_dpp v112, v112, v112 quad_perm:[1,0,3,2] row_mask:0xf bank_mask:0xf
	s_nop 1
	v_add_f32_dpp v112, v112, v112 quad_perm:[2,3,0,1] row_mask:0xf bank_mask:0xf
	s_nop 1
	v_add_f32_dpp v112, v112, v112 row_half_mirror row_mask:0xf bank_mask:0xf
	s_nop 1
	v_add_f32_dpp v112, v112, v112 row_mirror row_mask:0xf bank_mask:0xf
	s_nop 1
	v_add_f32_dpp v112, v112, v112 row_bcast:15 row_mask:0xa bank_mask:0xf
	s_nop 1
	v_add_f32_dpp v112, v112, v112 row_bcast:31 row_mask:0xc bank_mask:0xf
	s_nop 1
	v_readlane_b32 s2, v112, 63
	s_nop 1
	v_mov_b32_e32 v113, 0x358637bd
	v_mov_b32_e32 v114, 0x3a800000
	v_fmac_f32_e32 v113, s2, v114
	v_rsq_f32_e32 v115, v113
	v_mul_f32_e32 v113, 0.5, v113
	v_mul_f32_e32 v116, v115, v115
	v_mov_b32_e32 v117, 0x3fc00000
	v_fma_f32 v116, -v113, v116, v117
	v_mul_f32_e32 v144, v115, v116
	v_pk_mul_f32 v[32:33], v[32:33], v[144:145] op_sel_hi:[1,0]
	v_pk_mul_f32 v[34:35], v[34:35], v[144:145] op_sel_hi:[1,0]
	v_pk_mul_f32 v[36:37], v[36:37], v[144:145] op_sel_hi:[1,0]
	v_pk_mul_f32 v[38:39], v[38:39], v[144:145] op_sel_hi:[1,0]
	v_pk_mul_f32 v[40:41], v[40:41], v[144:145] op_sel_hi:[1,0]
	v_pk_mul_f32 v[42:43], v[42:43], v[144:145] op_sel_hi:[1,0]
	v_pk_mul_f32 v[44:45], v[44:45], v[144:145] op_sel_hi:[1,0]
	v_pk_mul_f32 v[46:47], v[46:47], v[144:145] op_sel_hi:[1,0]
	v_pk_fma_f32 v[32:33], v[64:65], v[32:33], v[48:49]
	v_pk_fma_f32 v[34:35], v[66:67], v[34:35], v[50:51]
	v_pk_fma_f32 v[36:37], v[68:69], v[36:37], v[52:53]
	v_pk_fma_f32 v[38:39], v[70:71], v[38:39], v[54:55]
	v_pk_fma_f32 v[40:41], v[72:73], v[40:41], v[56:57]
	v_pk_fma_f32 v[42:43], v[74:75], v[42:43], v[58:59]
	v_pk_fma_f32 v[44:45], v[76:77], v[44:45], v[60:61]
	v_pk_fma_f32 v[46:47], v[78:79], v[46:47], v[62:63]
	v_cvt_pk_bf16_f32 v120, v32, v33
	v_cvt_pk_bf16_f32 v121, v34, v35
	v_cvt_pk_bf16_f32 v122, v36, v37
	v_cvt_pk_bf16_f32 v123, v38, v39
	v_cvt_pk_bf16_f32 v124, v40, v41
	v_cvt_pk_bf16_f32 v125, v42, v43
	v_cvt_pk_bf16_f32 v126, v44, v45
	v_cvt_pk_bf16_f32 v127, v46, v47
	v_cndmask_b32_e64 v112, v122, v120, s[40:41]
	v_cndmask_b32_e64 v113, v123, v121, s[40:41]
	v_cndmask_b32_e64 v114, v126, v124, s[40:41]
	v_cndmask_b32_e64 v115, v127, v125, s[40:41]
	v_mov_b32_dpp v116, v112 quad_perm:[1,0,3,2] row_mask:0xf bank_mask:0xf
	v_mov_b32_dpp v117, v113 quad_perm:[1,0,3,2] row_mask:0xf bank_mask:0xf
	v_mov_b32_dpp v118, v114 quad_perm:[1,0,3,2] row_mask:0xf bank_mask:0xf
	v_mov_b32_dpp v119, v115 quad_perm:[1,0,3,2] row_mask:0xf bank_mask:0xf
	s_nop 0
	v_cndmask_b32_e64 v160, v120, v116, s[40:41]
	v_cndmask_b32_e64 v161, v121, v117, s[40:41]
	v_cndmask_b32_e64 v162, v116, v122, s[40:41]
	v_cndmask_b32_e64 v163, v117, v123, s[40:41]
	v_cndmask_b32_e64 v164, v124, v118, s[40:41]
	v_cndmask_b32_e64 v165, v125, v119, s[40:41]
	v_cndmask_b32_e64 v166, v118, v126, s[40:41]
	v_cndmask_b32_e64 v167, v119, v127, s[40:41]
	global_store_dwordx4 v[132:133], v[160:163], off sc1
	global_store_dwordx4 v[132:133], v[164:167], off offset:1024 sc1
	v_lshl_add_u64 v[132:133], v[132:133], 0, v[154:155]
	s_add_i32 s0, s0, 1
	s_cmp_lt_i32 s0, 3
	s_cbranch_scc1 .Lln0_loop

.Lln1a_loop:
	global_load_dwordx4 v[48:51], v[134:135], off offset:-4096
	global_load_dwordx4 v[52:55], v[134:135], off offset:-3072
	global_load_dwordx4 v[56:59], v[134:135], off offset:-2048
	global_load_dwordx4 v[60:63], v[134:135], off offset:-1024
	global_load_dwordx4 v[64:67], v[134:135], off
	global_load_dwordx4 v[68:71], v[134:135], off offset:1024
	global_load_dwordx4 v[72:75], v[134:135], off offset:2048
	global_load_dwordx4 v[76:79], v[134:135], off offset:3072
	v_lshl_add_u64 v[134:135], v[134:135], 0, v[156:157]
	global_load_dwordx4 v[32:35], v[128:129], off nt
	global_load_dwordx4 v[36:39], v[128:129], off offset:1024 nt
	global_load_dwordx4 v[40:43], v[128:129], off offset:2048 nt
	global_load_dwordx4 v[44:47], v[128:129], off offset:3072 nt
	v_lshl_add_u64 v[128:129], v[128:129], 0, v[152:153]
	s_waitcnt vmcnt(28)
	v_add_f32_e32 v112, v0, v1
	v_add_f32_e32 v113, v2, v3
	v_add_f32_e32 v114, v4, v5
	v_add_f32_e32 v115, v6, v7
	v_add_f32_e32 v116, v8, v9
	v_add_f32_e32 v117, v10, v11
	v_add_f32_e32 v118, v12, v13
	v_add_f32_e32 v119, v14, v15
	v_add_f32_e32 v112, v112, v116
	v_add_f32_e32 v113, v113, v117
	v_add_f32_e32 v114, v114, v118
	v_add_f32_e32 v115, v115, v119
	v_add_f32_e32 v112, v112, v113
	v_add_f32_e32 v114, v114, v115
	v_add_f32_e32 v112, v112, v114
	s_nop 1
	v_add_f32_dpp v112, v112, v112 quad_perm:[1,0,3,2] row_mask:0xf bank_mask:0xf
	s_nop 1
	v_add_f32_dpp v112, v112, v112 quad_perm:[2,3,0,1] row_mask:0xf bank_mask:0xf
	s_nop 1
	v_add_f32_dpp v112, v112, v112 row_half_mirror row_mask:0xf bank_mask:0xf
	s_nop 1
	v_add_f32_dpp v112, v112, v112 row_mirror row_mask:0xf bank_mask:0xf
	s_nop 1
	v_add_f32_dpp v112, v112, v112 row_bcast:15 row_mask:0xa bank_mask:0xf
	s_nop 1
	v_add_f32_dpp v112, v112, v112 row_bcast:31 row_mask:0xc bank_mask:0xf
	s_nop 1
	v_readlane_b32 s2, v112, 63
	s_nop 1
	v_fmac_f32_e32 v0, s2, v142
	v_fmac_f32_e32 v1, s2, v142
	v_fmac_f32_e32 v2, s2, v142
	v_fmac_f32_e32 v3, s2, v142
	v_fmac_f32_e32 v4, s2, v142
	v_fmac_f32_e32 v5, s2, v142
	v_fmac_f32_e32 v6, s2, v142
	v_fmac_f32_e32 v7, s2, v142
	v_fmac_f32_e32 v8, s2, v142
	v_fmac_f32_e32 v9, s2, v142
	v_fmac_f32_e32 v10, s2, v142
	v_fmac_f32_e32 v11, s2, v142
	v_fmac_f32_e32 v12, s2, v142
	v_fmac_f32_e32 v13, s2, v142
	v_fmac_f32_e32 v14, s2, v142
	v_fmac_f32_e32 v15, s2, v142
	v_mul_f32_e32 v112, v0, v0
	v_mul_f32_e32 v113, v1, v1
	v_mul_f32_e32 v114, v2, v2
	v_mul_f32_e32 v115, v3, v3
	v_fmac_f32_e32 v112, v4, v4
	v_fmac_f32_e32 v113, v5, v5
	v_fmac_f32_e32 v114, v6, v6
	v_fmac_f32_e32 v115, v7, v7
	v_fmac_f32_e32 v112, v8, v8
	v_fmac_f32_e32 v113, v9, v9
	v_fmac_f32_e32 v114, v10, v10
	v_fmac_f32_e32 v115, v11, v11
	v_fmac_f32_e32 v112, v12, v12
	v_fmac_f32_e32 v113, v13, v13
	v_fmac_f32_e32 v114, v14, v14
	v_fmac_f32_e32 v115, v15, v15
	v_add_f32_e32 v112, v112, v113
	v_add_f32_e32 v114, v114, v115
	v_add_f32_e32 v112, v112, v114
	s_nop 1
	v_add_f32_dpp v112, v112, v112 quad_perm:[1,0,3,2] row_mask:0xf bank_mask:0xf
	s_nop 1
	v_add_f32_dpp v112, v112, v112 quad_perm:[2,3,0,1] row_mask:0xf bank_mask:0xf
	s_nop 1
	v_add_f32_dpp v112, v112, v112 row_half_mirror row_mask:0xf bank_mask:0xf
	s_nop 1
	v_add_f32_dpp v112, v112, v112 row_mirror row_mask:0xf bank_mask:0xf
	s_nop 1
	v_add_f32_dpp v112, v112, v112 row_bcast:15 row_mask:0xa bank_mask:0xf
	s_nop 1
	v_add_f32_dpp v112, v112, v112 row_bcast:31 row_mask:0xc bank_mask:0xf
	s_nop 1
	v_readlane_b32 s2, v112, 63
	s_nop 1
	v_mov_b32_e32 v113, 0x358637bd
	v_mov_b32_e32 v114, 0x3a800000
	v_fmac_f32_e32 v113, s2, v114
	v_rsq_f32_e32 v115, v113
	v_mul_f32_e32 v113, 0.5, v113
	v_mul_f32_e32 v116, v115, v115
	v_mov_b32_e32 v117, 0x3fc00000
	v_fma_f32 v116, -v113, v116, v117
	v_mul_f32_e32 v144, v115, v116
	v_pk_mul_f32 v[0:1], v[0:1], v[144:145] op_sel_hi:[1,0]
	v_pk_mul_f32 v[2:3], v[2:3], v[144:145] op_sel_hi:[1,0]
	v_pk_mul_f32 v[4:5], v[4:5], v[144:145] op_sel_hi:[1,0]
	v_pk_mul_f32 v[6:7], v[6:7], v[144:145] op_sel_hi:[1,0]
	v_pk_mul_f32 v[8:9], v[8:9], v[144:145] op_sel_hi:[1,0]
	v_pk_mul_f32 v[10:11], v[10:11], v[144:145] op_sel_hi:[1,0]
	v_pk_mul_f32 v[12:13], v[12:13], v[144:145] op_sel_hi:[1,0]
	v_pk_mul_f32 v[14:15], v[14:15], v[144:145] op_sel_hi:[1,0]
	v_pk_fma_f32 v[0:1], v[80:81], v[0:1], v[96:97]
	v_pk_fma_f32 v[2:3], v[82:83], v[2:3], v[98:99]
	v_pk_fma_f32 v[4:5], v[84:85], v[4:5], v[100:101]
	v_pk_fma_f32 v[6:7], v[86:87], v[6:7], v[102:103]
	v_pk_fma_f32 v[8:9], v[88:89], v[8:9], v[104:105]
	v_pk_fma_f32 v[10:11], v[90:91], v[10:11], v[106:107]
	v_pk_fma_f32 v[12:13], v[92:93], v[12:13], v[108:109]
	v_pk_fma_f32 v[14:15], v[94:95], v[14:15], v[110:111]
	global_store_dwordx4 v[130:131], v[0:3], off sc1
	global_store_dwordx4 v[130:131], v[4:7], off offset:1024 sc1
	global_store_dwordx4 v[130:131], v[8:11], off offset:2048 sc1
	global_store_dwordx4 v[130:131], v[12:15], off offset:3072 sc1
	v_lshl_add_u64 v[130:131], v[130:131], 0, v[152:153]
	v_add_f32_e32 v112, v0, v1
	v_add_f32_e32 v113, v2, v3
	v_add_f32_e32 v114, v4, v5
	v_add_f32_e32 v115, v6, v7
	v_add_f32_e32 v116, v8, v9
	v_add_f32_e32 v117, v10, v11
	v_add_f32_e32 v118, v12, v13
	v_add_f32_e32 v119, v14, v15
	v_add_f32_e32 v112, v112, v116
	v_add_f32_e32 v113, v113, v117
	v_add_f32_e32 v114, v114, v118
	v_add_f32_e32 v115, v115, v119
	v_add_f32_e32 v112, v112, v113
	v_add_f32_e32 v114, v114, v115
	v_add_f32_e32 v112, v112, v114
	s_nop 1
	v_add_f32_dpp v112, v112, v112 quad_perm:[1,0,3,2] row_mask:0xf bank_mask:0xf
	s_nop 1
	v_add_f32_dpp v112, v112, v112 quad_perm:[2,3,0,1] row_mask:0xf bank_mask:0xf
	s_nop 1
	v_add_f32_dpp v112, v112, v112 row_half_mirror row_mask:0xf bank_mask:0xf
	s_nop 1
	v_add_f32_dpp v112, v112, v112 row_mirror row_mask:0xf bank_mask:0xf
	s_nop 1
	v_add_f32_dpp v112, v112, v112 row_bcast:15 row_mask:0xa bank_mask:0xf
	s_nop 1
	v_add_f32_dpp v112, v112, v112 row_bcast:31 row_mask:0xc bank_mask:0xf
	s_nop 1
	v_readlane_b32 s2, v112, 63
	s_nop 1
	v_fmac_f32_e32 v0, s2, v142
	v_fmac_f32_e32 v1, s2, v142
	v_fmac_f32_e32 v2, s2, v142
	v_fmac_f32_e32 v3, s2, v142
	v_fmac_f32_e32 v4, s2, v142
	v_fmac_f32_e32 v5, s2, v142
	v_fmac_f32_e32 v6, s2, v142
	v_fmac_f32_e32 v7, s2, v142
	v_fmac_f32_e32 v8, s2, v142
	v_fmac_f32_e32 v9, s2, v142
	v_fmac_f32_e32 v10, s2, v142
	v_fmac_f32_e32 v11, s2, v142
	v_fmac_f32_e32 v12, s2, v142
	v_fmac_f32_e32 v13, s2, v142
	v_fmac_f32_e32 v14, s2, v142
	v_fmac_f32_e32 v15, s2, v142
	v_mul_f32_e32 v112, v0, v0
	v_mul_f32_e32 v113, v1, v1
	v_mul_f32_e32 v114, v2, v2
	v_mul_f32_e32 v115, v3, v3
	v_fmac_f32_e32 v112, v4, v4
	v_fmac_f32_e32 v113, v5, v5
	v_fmac_f32_e32 v114, v6, v6
	v_fmac_f32_e32 v115, v7, v7
	v_fmac_f32_e32 v112, v8, v8
	v_fmac_f32_e32 v113, v9, v9
	v_fmac_f32_e32 v114, v10, v10
	v_fmac_f32_e32 v115, v11, v11
	v_fmac_f32_e32 v112, v12, v12
	v_fmac_f32_e32 v113, v13, v13
	v_fmac_f32_e32 v114, v14, v14
	v_fmac_f32_e32 v115, v15, v15
	v_add_f32_e32 v112, v112, v113
	v_add_f32_e32 v114, v114, v115
	v_add_f32_e32 v112, v112, v114
	s_nop 1
	v_add_f32_dpp v112, v112, v112 quad_perm:[1,0,3,2] row_mask:0xf bank_mask:0xf
	s_nop 1
	v_add_f32_dpp v112, v112, v112 quad_perm:[2,3,0,1] row_mask:0xf bank_mask:0xf
	s_nop 1
	v_add_f32_dpp v112, v112, v112 row_half_mirror row_mask:0xf bank_mask:0xf
	s_nop 1
	v_add_f32_dpp v112, v112, v112 row_mirror row_mask:0xf bank_mask:0xf
	s_nop 1
	v_add_f32_dpp v112, v112, v112 row_bcast:15 row_mask:0xa bank_mask:0xf
	s_nop 1
	v_add_f32_dpp v112, v112, v112 row_bcast:31 row_mask:0xc bank_mask:0xf
	s_nop 1
	v_readlane_b32 s2, v112, 63
	s_nop 1
	v_mov_b32_e32 v113, 0x358637bd
	v_mov_b32_e32 v114, 0x3a800000
	v_fmac_f32_e32 v113, s2, v114
	v_rsq_f32_e32 v115, v113
	v_mul_f32_e32 v113, 0.5, v113
	v_mul_f32_e32 v116, v115, v115
	v_mov_b32_e32 v117, 0x3fc00000
	v_fma_f32 v116, -v113, v116, v117
	v_mul_f32_e32 v144, v115, v116
	v_pk_mul_f32 v[0:1], v[0:1], v[144:145] op_sel_hi:[1,0]
	v_pk_mul_f32 v[2:3], v[2:3], v[144:145] op_sel_hi:[1,0]
	v_pk_mul_f32 v[4:5], v[4:5], v[144:145] op_sel_hi:[1,0]
	v_pk_mul_f32 v[6:7], v[6:7], v[144:145] op_sel_hi:[1,0]
	v_pk_mul_f32 v[8:9], v[8:9], v[144:145] op_sel_hi:[1,0]
	v_pk_mul_f32 v[10:11], v[10:11], v[144:145] op_sel_hi:[1,0]
	v_pk_mul_f32 v[12:13], v[12:13], v[144:145] op_sel_hi:[1,0]
	v_pk_mul_f32 v[14:15], v[14:15], v[144:145] op_sel_hi:[1,0]
	s_waitcnt vmcnt(8)
	v_pk_add_f32 v[64:65], v[64:65], 1.0 op_sel_hi:[1,0]
	v_pk_add_f32 v[66:67], v[66:67], 1.0 op_sel_hi:[1,0]
	v_pk_add_f32 v[68:69], v[68:69], 1.0 op_sel_hi:[1,0]
	v_pk_add_f32 v[70:71], v[70:71], 1.0 op_sel_hi:[1,0]
	v_pk_add_f32 v[72:73], v[72:73], 1.0 op_sel_hi:[1,0]
	v_pk_add_f32 v[74:75], v[74:75], 1.0 op_sel_hi:[1,0]
	v_pk_add_f32 v[76:77], v[76:77], 1.0 op_sel_hi:[1,0]
	v_pk_add_f32 v[78:79], v[78:79], 1.0 op_sel_hi:[1,0]
	v_pk_fma_f32 v[0:1], v[64:65], v[0:1], v[48:49]
	v_pk_fma_f32 v[2:3], v[66:67], v[2:3], v[50:51]
	v_pk_fma_f32 v[4:5], v[68:69], v[4:5], v[52:53]
	v_pk_fma_f32 v[6:7], v[70:71], v[6:7], v[54:55]
	v_pk_fma_f32 v[8:9], v[72:73], v[8:9], v[56:57]
	v_pk_fma_f32 v[10:11], v[74:75], v[10:11], v[58:59]
	v_pk_fma_f32 v[12:13], v[76:77], v[12:13], v[60:61]
	v_pk_fma_f32 v[14:15], v[78:79], v[14:15], v[62:63]
	v_cvt_pk_bf16_f32 v120, v0, v1
	v_cvt_pk_bf16_f32 v121, v2, v3
	v_cvt_pk_bf16_f32 v122, v4, v5
	v_cvt_pk_bf16_f32 v123, v6, v7
	v_cvt_pk_bf16_f32 v124, v8, v9
	v_cvt_pk_bf16_f32 v125, v10, v11
	v_cvt_pk_bf16_f32 v126, v12, v13
	v_cvt_pk_bf16_f32 v127, v14, v15
	v_cndmask_b32_e64 v112, v122, v120, s[40:41]
	v_cndmask_b32_e64 v113, v123, v121, s[40:41]
	v_cndmask_b32_e64 v114, v126, v124, s[40:41]
	v_cndmask_b32_e64 v115, v127, v125, s[40:41]
	v_mov_b32_dpp v116, v112 quad_perm:[1,0,3,2] row_mask:0xf bank_mask:0xf
	v_mov_b32_dpp v117, v113 quad_perm:[1,0,3,2] row_mask:0xf bank_mask:0xf
	v_mov_b32_dpp v118, v114 quad_perm:[1,0,3,2] row_mask:0xf bank_mask:0xf
	v_mov_b32_dpp v119, v115 quad_perm:[1,0,3,2] row_mask:0xf bank_mask:0xf
	s_nop 0
	v_cndmask_b32_e64 v160, v120, v116, s[40:41]
	v_cndmask_b32_e64 v161, v121, v117, s[40:41]
	v_cndmask_b32_e64 v162, v116, v122, s[40:41]
	v_cndmask_b32_e64 v163, v117, v123, s[40:41]
	v_cndmask_b32_e64 v164, v124, v118, s[40:41]
	v_cndmask_b32_e64 v165, v125, v119, s[40:41]
	v_cndmask_b32_e64 v166, v118, v126, s[40:41]
	v_cndmask_b32_e64 v167, v119, v127, s[40:41]
	global_store_dwordx4 v[132:133], v[160:163], off sc1
	global_store_dwordx4 v[132:133], v[164:167], off offset:1024 sc1
	v_lshl_add_u64 v[132:133], v[132:133], 0, v[154:155]
	global_load_dwordx4 v[0:3], v[128:129], off nt
	global_load_dwordx4 v[4:7], v[128:129], off offset:1024 nt
	global_load_dwordx4 v[8:11], v[128:129], off offset:2048 nt
	global_load_dwordx4 v[12:15], v[128:129], off offset:3072 nt
	v_lshl_add_u64 v[128:129], v[128:129], 0, v[152:153]
	v_add_f32_e32 v112, v16, v17
	v_add_f32_e32 v113, v18, v19
	v_add_f32_e32 v114, v20, v21
	v_add_f32_e32 v115, v22, v23
	v_add_f32_e32 v116, v24, v25
	v_add_f32_e32 v117, v26, v27
	v_add_f32_e32 v118, v28, v29
	v_add_f32_e32 v119, v30, v31
	v_add_f32_e32 v112, v112, v116
	v_add_f32_e32 v113, v113, v117
	v_add_f32_e32 v114, v114, v118
	v_add_f32_e32 v115, v115, v119
	v_add_f32_e32 v112, v112, v113
	v_add_f32_e32 v114, v114, v115
	v_add_f32_e32 v112, v112, v114
	s_nop 1
	v_add_f32_dpp v112, v112, v112 quad_perm:[1,0,3,2] row_mask:0xf bank_mask:0xf
	s_nop 1
	v_add_f32_dpp v112, v112, v112 quad_perm:[2,3,0,1] row_mask:0xf bank_mask:0xf
	s_nop 1
	v_add_f32_dpp v112, v112, v112 row_half_mirror row_mask:0xf bank_mask:0xf
	s_nop 1
	v_add_f32_dpp v112, v112, v112 row_mirror row_mask:0xf bank_mask:0xf
	s_nop 1
	v_add_f32_dpp v112, v112, v112 row_bcast:15 row_mask:0xa bank_mask:0xf
	s_nop 1
	v_add_f32_dpp v112, v112, v112 row_bcast:31 row_mask:0xc bank_mask:0xf
	s_nop 1
	v_readlane_b32 s2, v112, 63
	s_nop 1
	v_fmac_f32_e32 v16, s2, v142
	v_fmac_f32_e32 v17, s2, v142
	v_fmac_f32_e32 v18, s2, v142
	v_fmac_f32_e32 v19, s2, v142
	v_fmac_f32_e32 v20, s2, v142
	v_fmac_f32_e32 v21, s2, v142
	v_fmac_f32_e32 v22, s2, v142
	v_fmac_f32_e32 v23, s2, v142
	v_fmac_f32_e32 v24, s2, v142
	v_fmac_f32_e32 v25, s2, v142
	v_fmac_f32_e32 v26, s2, v142
	v_fmac_f32_e32 v27, s2, v142
	v_fmac_f32_e32 v28, s2, v142
	v_fmac_f32_e32 v29, s2, v142
	v_fmac_f32_e32 v30, s2, v142
	v_fmac_f32_e32 v31, s2, v142
	v_mul_f32_e32 v112, v16, v16
	v_mul_f32_e32 v113, v17, v17
	v_mul_f32_e32 v114, v18, v18
	v_mul_f32_e32 v115, v19, v19
	v_fmac_f32_e32 v112, v20, v20
	v_fmac_f32_e32 v113, v21, v21
	v_fmac_f32_e32 v114, v22, v22
	v_fmac_f32_e32 v115, v23, v23
	v_fmac_f32_e32 v112, v24, v24
	v_fmac_f32_e32 v113, v25, v25
	v_fmac_f32_e32 v114, v26, v26
	v_fmac_f32_e32 v115, v27, v27
	v_fmac_f32_e32 v112, v28, v28
	v_fmac_f32_e32 v113, v29, v29
	v_fmac_f32_e32 v114, v30, v30
	v_fmac_f32_e32 v115, v31, v31
	v_add_f32_e32 v112, v112, v113
	v_add_f32_e32 v114, v114, v115
	v_add_f32_e32 v112, v112, v114
	s_nop 1
	v_add_f32_dpp v112, v112, v112 quad_perm:[1,0,3,2] row_mask:0xf bank_mask:0xf
	s_nop 1
	v_add_f32_dpp v112, v112, v112 quad_perm:[2,3,0,1] row_mask:0xf bank_mask:0xf
	s_nop 1
	v_add_f32_dpp v112, v112, v112 row_half_mirror row_mask:0xf bank_mask:0xf
	s_nop 1
	v_add_f32_dpp v112, v112, v112 row_mirror row_mask:0xf bank_mask:0xf
	s_nop 1
	v_add_f32_dpp v112, v112, v112 row_bcast:15 row_mask:0xa bank_mask:0xf
	s_nop 1
	v_add_f32_dpp v112, v112, v112 row_bcast:31 row_mask:0xc bank_mask:0xf
	s_nop 1
	v_readlane_b32 s2, v112, 63
	s_nop 1
	v_mov_b32_e32 v113, 0x358637bd
	v_mov_b32_e32 v114, 0x3a800000
	v_fmac_f32_e32 v113, s2, v114
	v_rsq_f32_e32 v115, v113
	v_mul_f32_e32 v113, 0.5, v113
	v_mul_f32_e32 v116, v115, v115
	v_mov_b32_e32 v117, 0x3fc00000
	v_fma_f32 v116, -v113, v116, v117
	v_mul_f32_e32 v144, v115, v116
	v_pk_mul_f32 v[16:17], v[16:17], v[144:145] op_sel_hi:[1,0]
	v_pk_mul_f32 v[18:19], v[18:19], v[144:145] op_sel_hi:[1,0]
	v_pk_mul_f32 v[20:21], v[20:21], v[144:145] op_sel_hi:[1,0]
	v_pk_mul_f32 v[22:23], v[22:23], v[144:145] op_sel_hi:[1,0]
	v_pk_mul_f32 v[24:25], v[24:25], v[144:145] op_sel_hi:[1,0]
	v_pk_mul_f32 v[26:27], v[26:27], v[144:145] op_sel_hi:[1,0]
	v_pk_mul_f32 v[28:29], v[28:29], v[144:145] op_sel_hi:[1,0]
	v_pk_mul_f32 v[30:31], v[30:31], v[144:145] op_sel_hi:[1,0]
	v_pk_fma_f32 v[16:17], v[80:81], v[16:17], v[96:97]
	v_pk_fma_f32 v[18:19], v[82:83], v[18:19], v[98:99]
	v_pk_fma_f32 v[20:21], v[84:85], v[20:21], v[100:101]
	v_pk_fma_f32 v[22:23], v[86:87], v[22:23], v[102:103]
	v_pk_fma_f32 v[24:25], v[88:89], v[24:25], v[104:105]
	v_pk_fma_f32 v[26:27], v[90:91], v[26:27], v[106:107]
	v_pk_fma_f32 v[28:29], v[92:93], v[28:29], v[108:109]
	v_pk_fma_f32 v[30:31], v[94:95], v[30:31], v[110:111]
	global_store_dwordx4 v[130:131], v[16:19], off sc1
	global_store_dwordx4 v[130:131], v[20:23], off offset:1024 sc1
	global_store_dwordx4 v[130:131], v[24:27], off offset:2048 sc1
	global_store_dwordx4 v[130:131], v[28:31], off offset:3072 sc1
	v_lshl_add_u64 v[130:131], v[130:131], 0, v[152:153]
	v_add_f32_e32 v112, v16, v17
	v_add_f32_e32 v113, v18, v19
	v_add_f32_e32 v114, v20, v21
	v_add_f32_e32 v115, v22, v23
	v_add_f32_e32 v116, v24, v25
	v_add_f32_e32 v117, v26, v27
	v_add_f32_e32 v118, v28, v29
	v_add_f32_e32 v119, v30, v31
	v_add_f32_e32 v112, v112, v116
	v_add_f32_e32 v113, v113, v117
	v_add_f32_e32 v114, v114, v118
	v_add_f32_e32 v115, v115, v119
	v_add_f32_e32 v112, v112, v113
	v_add_f32_e32 v114, v114, v115
	v_add_f32_e32 v112, v112, v114
	s_nop 1
	v_add_f32_dpp v112, v112, v112 quad_perm:[1,0,3,2] row_mask:0xf bank_mask:0xf
	s_nop 1
	v_add_f32_dpp v112, v112, v112 quad_perm:[2,3,0,1] row_mask:0xf bank_mask:0xf
	s_nop 1
	v_add_f32_dpp v112, v112, v112 row_half_mirror row_mask:0xf bank_mask:0xf
	s_nop 1
	v_add_f32_dpp v112, v112, v112 row_mirror row_mask:0xf bank_mask:0xf
	s_nop 1
	v_add_f32_dpp v112, v112, v112 row_bcast:15 row_mask:0xa bank_mask:0xf
	s_nop 1
	v_add_f32_dpp v112, v112, v112 row_bcast:31 row_mask:0xc bank_mask:0xf
	s_nop 1
	v_readlane_b32 s2, v112, 63
	s_nop 1
	v_fmac_f32_e32 v16, s2, v142
	v_fmac_f32_e32 v17, s2, v142
	v_fmac_f32_e32 v18, s2, v142
	v_fmac_f32_e32 v19, s2, v142
	v_fmac_f32_e32 v20, s2, v142
	v_fmac_f32_e32 v21, s2, v142
	v_fmac_f32_e32 v22, s2, v142
	v_fmac_f32_e32 v23, s2, v142
	v_fmac_f32_e32 v24, s2, v142
	v_fmac_f32_e32 v25, s2, v142
	v_fmac_f32_e32 v26, s2, v142
	v_fmac_f32_e32 v27, s2, v142
	v_fmac_f32_e32 v28, s2, v142
	v_fmac_f32_e32 v29, s2, v142
	v_fmac_f32_e32 v30, s2, v142
	v_fmac_f32_e32 v31, s2, v142
	v_mul_f32_e32 v112, v16, v16
	v_mul_f32_e32 v113, v17, v17
	v_mul_f32_e32 v114, v18, v18
	v_mul_f32_e32 v115, v19, v19
	v_fmac_f32_e32 v112, v20, v20
	v_fmac_f32_e32 v113, v21, v21
	v_fmac_f32_e32 v114, v22, v22
	v_fmac_f32_e32 v115, v23, v23
	v_fmac_f32_e32 v112, v24, v24
	v_fmac_f32_e32 v113, v25, v25
	v_fmac_f32_e32 v114, v26, v26
	v_fmac_f32_e32 v115, v27, v27
	v_fmac_f32_e32 v112, v28, v28
	v_fmac_f32_e32 v113, v29, v29
	v_fmac_f32_e32 v114, v30, v30
	v_fmac_f32_e32 v115, v31, v31
	v_add_f32_e32 v112, v112, v113
	v_add_f32_e32 v114, v114, v115
	v_add_f32_e32 v112, v112, v114
	s_nop 1
	v_add_f32_dpp v112, v112, v112 quad_perm:[1,0,3,2] row_mask:0xf bank_mask:0xf
	s_nop 1
	v_add_f32_dpp v112, v112, v112 quad_perm:[2,3,0,1] row_mask:0xf bank_mask:0xf
	s_nop 1
	v_add_f32_dpp v112, v112, v112 row_half_mirror row_mask:0xf bank_mask:0xf
	s_nop 1
	v_add_f32_dpp v112, v112, v112 row_mirror row_mask:0xf bank_mask:0xf
	s_nop 1
	v_add_f32_dpp v112, v112, v112 row_bcast:15 row_mask:0xa bank_mask:0xf
	s_nop 1
	v_add_f32_dpp v112, v112, v112 row_bcast:31 row_mask:0xc bank_mask:0xf
	s_nop 1
	v_readlane_b32 s2, v112, 63
	s_nop 1
	v_mov_b32_e32 v113, 0x358637bd
	v_mov_b32_e32 v114, 0x3a800000
	v_fmac_f32_e32 v113, s2, v114
	v_rsq_f32_e32 v115, v113
	v_mul_f32_e32 v113, 0.5, v113
	v_mul_f32_e32 v116, v115, v115
	v_mov_b32_e32 v117, 0x3fc00000
	v_fma_f32 v116, -v113, v116, v117
	v_mul_f32_e32 v144, v115, v116
	v_pk_mul_f32 v[16:17], v[16:17], v[144:145] op_sel_hi:[1,0]
	v_pk_mul_f32 v[18:19], v[18:19], v[144:145] op_sel_hi:[1,0]
	v_pk_mul_f32 v[20:21], v[20:21], v[144:145] op_sel_hi:[1,0]
	v_pk_mul_f32 v[22:23], v[22:23], v[144:145] op_sel_hi:[1,0]
	v_pk_mul_f32 v[24:25], v[24:25], v[144:145] op_sel_hi:[1,0]
	v_pk_mul_f32 v[26:27], v[26:27], v[144:145] op_sel_hi:[1,0]
	v_pk_mul_f32 v[28:29], v[28:29], v[144:145] op_sel_hi:[1,0]
	v_pk_mul_f32 v[30:31], v[30:31], v[144:145] op_sel_hi:[1,0]
	v_pk_fma_f32 v[16:17], v[64:65], v[16:17], v[48:49]
	v_pk_fma_f32 v[18:19], v[66:67], v[18:19], v[50:51]
	v_pk_fma_f32 v[20:21], v[68:69], v[20:21], v[52:53]
	v_pk_fma_f32 v[22:23], v[70:71], v[22:23], v[54:55]
	v_pk_fma_f32 v[24:25], v[72:73], v[24:25], v[56:57]
	v_pk_fma_f32 v[26:27], v[74:75], v[26:27], v[58:59]
	v_pk_fma_f32 v[28:29], v[76:77], v[28:29], v[60:61]
	v_pk_fma_f32 v[30:31], v[78:79], v[30:31], v[62:63]
	v_cvt_pk_bf16_f32 v120, v16, v17
	v_cvt_pk_bf16_f32 v121, v18, v19
	v_cvt_pk_bf16_f32 v122, v20, v21
	v_cvt_pk_bf16_f32 v123, v22, v23
	v_cvt_pk_bf16_f32 v124, v24, v25
	v_cvt_pk_bf16_f32 v125, v26, v27
	v_cvt_pk_bf16_f32 v126, v28, v29
	v_cvt_pk_bf16_f32 v127, v30, v31
	v_cndmask_b32_e64 v112, v122, v120, s[40:41]
	v_cndmask_b32_e64 v113, v123, v121, s[40:41]
	v_cndmask_b32_e64 v114, v126, v124, s[40:41]
	v_cndmask_b32_e64 v115, v127, v125, s[40:41]
	v_mov_b32_dpp v116, v112 quad_perm:[1,0,3,2] row_mask:0xf bank_mask:0xf
	v_mov_b32_dpp v117, v113 quad_perm:[1,0,3,2] row_mask:0xf bank_mask:0xf
	v_mov_b32_dpp v118, v114 quad_perm:[1,0,3,2] row_mask:0xf bank_mask:0xf
	v_mov_b32_dpp v119, v115 quad_perm:[1,0,3,2] row_mask:0xf bank_mask:0xf
	s_nop 0
	v_cndmask_b32_e64 v160, v120, v116, s[40:41]
	v_cndmask_b32_e64 v161, v121, v117, s[40:41]
	v_cndmask_b32_e64 v162, v116, v122, s[40:41]
	v_cndmask_b32_e64 v163, v117, v123, s[40:41]
	v_cndmask_b32_e64 v164, v124, v118, s[40:41]
	v_cndmask_b32_e64 v165, v125, v119, s[40:41]
	v_cndmask_b32_e64 v166, v118, v126, s[40:41]
	v_cndmask_b32_e64 v167, v119, v127, s[40:41]
	global_store_dwordx4 v[132:133], v[160:163], off sc1
	global_store_dwordx4 v[132:133], v[164:167], off offset:1024 sc1
	v_lshl_add_u64 v[132:133], v[132:133], 0, v[154:155]
	global_load_dwordx4 v[48:51], v[134:135], off offset:-4096
	global_load_dwordx4 v[52:55], v[134:135], off offset:-3072
	global_load_dwordx4 v[56:59], v[134:135], off offset:-2048
	global_load_dwordx4 v[60:63], v[134:135], off offset:-1024
	global_load_dwordx4 v[64:67], v[134:135], off
	global_load_dwordx4 v[68:71], v[134:135], off offset:1024
	global_load_dwordx4 v[72:75], v[134:135], off offset:2048
	global_load_dwordx4 v[76:79], v[134:135], off offset:3072
	v_lshl_add_u64 v[134:135], v[134:135], 0, v[156:157]
	global_load_dwordx4 v[16:19], v[128:129], off nt
	global_load_dwordx4 v[20:23], v[128:129], off offset:1024 nt
	global_load_dwordx4 v[24:27], v[128:129], off offset:2048 nt
	global_load_dwordx4 v[28:31], v[128:129], off offset:3072 nt
	v_lshl_add_u64 v[128:129], v[128:129], 0, v[152:153]
	s_waitcnt vmcnt(28)
	v_add_f32_e32 v112, v32, v33
	v_add_f32_e32 v113, v34, v35
	v_add_f32_e32 v114, v36, v37
	v_add_f32_e32 v115, v38, v39
	v_add_f32_e32 v116, v40, v41
	v_add_f32_e32 v117, v42, v43
	v_add_f32_e32 v118, v44, v45
	v_add_f32_e32 v119, v46, v47
	v_add_f32_e32 v112, v112, v116
	v_add_f32_e32 v113, v113, v117
	v_add_f32_e32 v114, v114, v118
	v_add_f32_e32 v115, v115, v119
	v_add_f32_e32 v112, v112, v113
	v_add_f32_e32 v114, v114, v115
	v_add_f32_e32 v112, v112, v114
	s_nop 1
	v_add_f32_dpp v112, v112, v112 quad_perm:[1,0,3,2] row_mask:0xf bank_mask:0xf
	s_nop 1
	v_add_f32_dpp v112, v112, v112 quad_perm:[2,3,0,1] row_mask:0xf bank_mask:0xf
	s_nop 1
	v_add_f32_dpp v112, v112, v112 row_half_mirror row_mask:0xf bank_mask:0xf
	s_nop 1
	v_add_f32_dpp v112, v112, v112 row_mirror row_mask:0xf bank_mask:0xf
	s_nop 1
	v_add_f32_dpp v112, v112, v112 row_bcast:15 row_mask:0xa bank_mask:0xf
	s_nop 1
	v_add_f32_dpp v112, v112, v112 row_bcast:31 row_mask:0xc bank_mask:0xf
	s_nop 1
	v_readlane_b32 s2, v112, 63
	s_nop 1
	v_fmac_f32_e32 v32, s2, v142
	v_fmac_f32_e32 v33, s2, v142
	v_fmac_f32_e32 v34, s2, v142
	v_fmac_f32_e32 v35, s2, v142
	v_fmac_f32_e32 v36, s2, v142
	v_fmac_f32_e32 v37, s2, v142
	v_fmac_f32_e32 v38, s2, v142
	v_fmac_f32_e32 v39, s2, v142
	v_fmac_f32_e32 v40, s2, v142
	v_fmac_f32_e32 v41, s2, v142
	v_fmac_f32_e32 v42, s2, v142
	v_fmac_f32_e32 v43, s2, v142
	v_fmac_f32_e32 v44, s2, v142
	v_fmac_f32_e32 v45, s2, v142
	v_fmac_f32_e32 v46, s2, v142
	v_fmac_f32_e32 v47, s2, v142
	v_mul_f32_e32 v112, v32, v32
	v_mul_f32_e32 v113, v33, v33
	v_mul_f32_e32 v114, v34, v34
	v_mul_f32_e32 v115, v35, v35
	v_fmac_f32_e32 v112, v36, v36
	v_fmac_f32_e32 v113, v37, v37
	v_fmac_f32_e32 v114, v38, v38
	v_fmac_f32_e32 v115, v39, v39
	v_fmac_f32_e32 v112, v40, v40
	v_fmac_f32_e32 v113, v41, v41
	v_fmac_f32_e32 v114, v42, v42
	v_fmac_f32_e32 v115, v43, v43
	v_fmac_f32_e32 v112, v44, v44
	v_fmac_f32_e32 v113, v45, v45
	v_fmac_f32_e32 v114, v46, v46
	v_fmac_f32_e32 v115, v47, v47
	v_add_f32_e32 v112, v112, v113
	v_add_f32_e32 v114, v114, v115
	v_add_f32_e32 v112, v112, v114
	s_nop 1
	v_add_f32_dpp v112, v112, v112 quad_perm:[1,0,3,2] row_mask:0xf bank_mask:0xf
	s_nop 1
	v_add_f32_dpp v112, v112, v112 quad_perm:[2,3,0,1] row_mask:0xf bank_mask:0xf
	s_nop 1
	v_add_f32_dpp v112, v112, v112 row_half_mirror row_mask:0xf bank_mask:0xf
	s_nop 1
	v_add_f32_dpp v112, v112, v112 row_mirror row_mask:0xf bank_mask:0xf
	s_nop 1
	v_add_f32_dpp v112, v112, v112 row_bcast:15 row_mask:0xa bank_mask:0xf
	s_nop 1
	v_add_f32_dpp v112, v112, v112 row_bcast:31 row_mask:0xc bank_mask:0xf
	s_nop 1
	v_readlane_b32 s2, v112, 63
	s_nop 1
	v_mov_b32_e32 v113, 0x358637bd
	v_mov_b32_e32 v114, 0x3a800000
	v_fmac_f32_e32 v113, s2, v114
	v_rsq_f32_e32 v115, v113
	v_mul_f32_e32 v113, 0.5, v113
	v_mul_f32_e32 v116, v115, v115
	v_mov_b32_e32 v117, 0x3fc00000
	v_fma_f32 v116, -v113, v116, v117
	v_mul_f32_e32 v144, v115, v116
	v_pk_mul_f32 v[32:33], v[32:33], v[144:145] op_sel_hi:[1,0]
	v_pk_mul_f32 v[34:35], v[34:35], v[144:145] op_sel_hi:[1,0]
	v_pk_mul_f32 v[36:37], v[36:37], v[144:145] op_sel_hi:[1,0]
	v_pk_mul_f32 v[38:39], v[38:39], v[144:145] op_sel_hi:[1,0]
	v_pk_mul_f32 v[40:41], v[40:41], v[144:145] op_sel_hi:[1,0]
	v_pk_mul_f32 v[42:43], v[42:43], v[144:145] op_sel_hi:[1,0]
	v_pk_mul_f32 v[44:45], v[44:45], v[144:145] op_sel_hi:[1,0]
	v_pk_mul_f32 v[46:47], v[46:47], v[144:145] op_sel_hi:[1,0]
	v_pk_fma_f32 v[32:33], v[80:81], v[32:33], v[96:97]
	v_pk_fma_f32 v[34:35], v[82:83], v[34:35], v[98:99]
	v_pk_fma_f32 v[36:37], v[84:85], v[36:37], v[100:101]
	v_pk_fma_f32 v[38:39], v[86:87], v[38:39], v[102:103]
	v_pk_fma_f32 v[40:41], v[88:89], v[40:41], v[104:105]
	v_pk_fma_f32 v[42:43], v[90:91], v[42:43], v[106:107]
	v_pk_fma_f32 v[44:45], v[92:93], v[44:45], v[108:109]
	v_pk_fma_f32 v[46:47], v[94:95], v[46:47], v[110:111]
	global_store_dwordx4 v[130:131], v[32:35], off sc1
	global_store_dwordx4 v[130:131], v[36:39], off offset:1024 sc1
	global_store_dwordx4 v[130:131], v[40:43], off offset:2048 sc1
	global_store_dwordx4 v[130:131], v[44:47], off offset:3072 sc1
	v_lshl_add_u64 v[130:131], v[130:131], 0, v[152:153]
	v_add_f32_e32 v112, v32, v33
	v_add_f32_e32 v113, v34, v35
	v_add_f32_e32 v114, v36, v37
	v_add_f32_e32 v115, v38, v39
	v_add_f32_e32 v116, v40, v41
	v_add_f32_e32 v117, v42, v43
	v_add_f32_e32 v118, v44, v45
	v_add_f32_e32 v119, v46, v47
	v_add_f32_e32 v112, v112, v116
	v_add_f32_e32 v113, v113, v117
	v_add_f32_e32 v114, v114, v118
	v_add_f32_e32 v115, v115, v119
	v_add_f32_e32 v112, v112, v113
	v_add_f32_e32 v114, v114, v115
	v_add_f32_e32 v112, v112, v114
	s_nop 1
	v_add_f32_dpp v112, v112, v112 quad_perm:[1,0,3,2] row_mask:0xf bank_mask:0xf
	s_nop 1
	v_add_f32_dpp v112, v112, v112 quad_perm:[2,3,0,1] row_mask:0xf bank_mask:0xf
	s_nop 1
	v_add_f32_dpp v112, v112, v112 row_half_mirror row_mask:0xf bank_mask:0xf
	s_nop 1
	v_add_f32_dpp v112, v112, v112 row_mirror row_mask:0xf bank_mask:0xf
	s_nop 1
	v_add_f32_dpp v112, v112, v112 row_bcast:15 row_mask:0xa bank_mask:0xf
	s_nop 1
	v_add_f32_dpp v112, v112, v112 row_bcast:31 row_mask:0xc bank_mask:0xf
	s_nop 1
	v_readlane_b32 s2, v112, 63
	s_nop 1
	v_fmac_f32_e32 v32, s2, v142
	v_fmac_f32_e32 v33, s2, v142
	v_fmac_f32_e32 v34, s2, v142
	v_fmac_f32_e32 v35, s2, v142
	v_fmac_f32_e32 v36, s2, v142
	v_fmac_f32_e32 v37, s2, v142
	v_fmac_f32_e32 v38, s2, v142
	v_fmac_f32_e32 v39, s2, v142
	v_fmac_f32_e32 v40, s2, v142
	v_fmac_f32_e32 v41, s2, v142
	v_fmac_f32_e32 v42, s2, v142
	v_fmac_f32_e32 v43, s2, v142
	v_fmac_f32_e32 v44, s2, v142
	v_fmac_f32_e32 v45, s2, v142
	v_fmac_f32_e32 v46, s2, v142
	v_fmac_f32_e32 v47, s2, v142
	v_mul_f32_e32 v112, v32, v32
	v_mul_f32_e32 v113, v33, v33
	v_mul_f32_e32 v114, v34, v34
	v_mul_f32_e32 v115, v35, v35
	v_fmac_f32_e32 v112, v36, v36
	v_fmac_f32_e32 v113, v37, v37
	v_fmac_f32_e32 v114, v38, v38
	v_fmac_f32_e32 v115, v39, v39
	v_fmac_f32_e32 v112, v40, v40
	v_fmac_f32_e32 v113, v41, v41
	v_fmac_f32_e32 v114, v42, v42
	v_fmac_f32_e32 v115, v43, v43
	v_fmac_f32_e32 v112, v44, v44
	v_fmac_f32_e32 v113, v45, v45
	v_fmac_f32_e32 v114, v46, v46
	v_fmac_f32_e32 v115, v47, v47
	v_add_f32_e32 v112, v112, v113
	v_add_f32_e32 v114, v114, v115
	v_add_f32_e32 v112, v112, v114
	s_nop 1
	v_add_f32_dpp v112, v112, v112 quad_perm:[1,0,3,2] row_mask:0xf bank_mask:0xf
	s_nop 1
	v_add_f32_dpp v112, v112, v112 quad_perm:[2,3,0,1] row_mask:0xf bank_mask:0xf
	s_nop 1
	v_add_f32_dpp v112, v112, v112 row_half_mirror row_mask:0xf bank_mask:0xf
	s_nop 1
	v_add_f32_dpp v112, v112, v112 row_mirror row_mask:0xf bank_mask:0xf
	s_nop 1
	v_add_f32_dpp v112, v112, v112 row_bcast:15 row_mask:0xa bank_mask:0xf
	s_nop 1
	v_add_f32_dpp v112, v112, v112 row_bcast:31 row_mask:0xc bank_mask:0xf
	s_nop 1
	v_readlane_b32 s2, v112, 63
	s_nop 1
	v_mov_b32_e32 v113, 0x358637bd
	v_mov_b32_e32 v114, 0x3a800000
	v_fmac_f32_e32 v113, s2, v114
	v_rsq_f32_e32 v115, v113
	v_mul_f32_e32 v113, 0.5, v113
	v_mul_f32_e32 v116, v115, v115
	v_mov_b32_e32 v117, 0x3fc00000
	v_fma_f32 v116, -v113, v116, v117
	v_mul_f32_e32 v144, v115, v116
	v_pk_mul_f32 v[32:33], v[32:33], v[144:145] op_sel_hi:[1,0]
	v_pk_mul_f32 v[34:35], v[34:35], v[144:145] op_sel_hi:[1,0]
	v_pk_mul_f32 v[36:37], v[36:37], v[144:145] op_sel_hi:[1,0]
	v_pk_mul_f32 v[38:39], v[38:39], v[144:145] op_sel_hi:[1,0]
	v_pk_mul_f32 v[40:41], v[40:41], v[144:145] op_sel_hi:[1,0]
	v_pk_mul_f32 v[42:43], v[42:43], v[144:145] op_sel_hi:[1,0]
	v_pk_mul_f32 v[44:45], v[44:45], v[144:145] op_sel_hi:[1,0]
	v_pk_mul_f32 v[46:47], v[46:47], v[144:145] op_sel_hi:[1,0]
	s_waitcnt vmcnt(8)
	v_pk_add_f32 v[64:65], v[64:65], 1.0 op_sel_hi:[1,0]
	v_pk_add_f32 v[66:67], v[66:67], 1.0 op_sel_hi:[1,0]
	v_pk_add_f32 v[68:69], v[68:69], 1.0 op_sel_hi:[1,0]
	v_pk_add_f32 v[70:71], v[70:71], 1.0 op_sel_hi:[1,0]
	v_pk_add_f32 v[72:73], v[72:73], 1.0 op_sel_hi:[1,0]
	v_pk_add_f32 v[74:75], v[74:75], 1.0 op_sel_hi:[1,0]
	v_pk_add_f32 v[76:77], v[76:77], 1.0 op_sel_hi:[1,0]
	v_pk_add_f32 v[78:79], v[78:79], 1.0 op_sel_hi:[1,0]
	v_pk_fma_f32 v[32:33], v[64:65], v[32:33], v[48:49]
	v_pk_fma_f32 v[34:35], v[66:67], v[34:35], v[50:51]
	v_pk_fma_f32 v[36:37], v[68:69], v[36:37], v[52:53]
	v_pk_fma_f32 v[38:39], v[70:71], v[38:39], v[54:55]
	v_pk_fma_f32 v[40:41], v[72:73], v[40:41], v[56:57]
	v_pk_fma_f32 v[42:43], v[74:75], v[42:43], v[58:59]
	v_pk_fma_f32 v[44:45], v[76:77], v[44:45], v[60:61]
	v_pk_fma_f32 v[46:47], v[78:79], v[46:47], v[62:63]
	v_cvt_pk_bf16_f32 v120, v32, v33
	v_cvt_pk_bf16_f32 v121, v34, v35
	v_cvt_pk_bf16_f32 v122, v36, v37
	v_cvt_pk_bf16_f32 v123, v38, v39
	v_cvt_pk_bf16_f32 v124, v40, v41
	v_cvt_pk_bf16_f32 v125, v42, v43
	v_cvt_pk_bf16_f32 v126, v44, v45
	v_cvt_pk_bf16_f32 v127, v46, v47
	v_cndmask_b32_e64 v112, v122, v120, s[40:41]
	v_cndmask_b32_e64 v113, v123, v121, s[40:41]
	v_cndmask_b32_e64 v114, v126, v124, s[40:41]
	v_cndmask_b32_e64 v115, v127, v125, s[40:41]
	v_mov_b32_dpp v116, v112 quad_perm:[1,0,3,2] row_mask:0xf bank_mask:0xf
	v_mov_b32_dpp v117, v113 quad_perm:[1,0,3,2] row_mask:0xf bank_mask:0xf
	v_mov_b32_dpp v118, v114 quad_perm:[1,0,3,2] row_mask:0xf bank_mask:0xf
	v_mov_b32_dpp v119, v115 quad_perm:[1,0,3,2] row_mask:0xf bank_mask:0xf
	s_nop 0
	v_cndmask_b32_e64 v160, v120, v116, s[40:41]
	v_cndmask_b32_e64 v161, v121, v117, s[40:41]
	v_cndmask_b32_e64 v162, v116, v122, s[40:41]
	v_cndmask_b32_e64 v163, v117, v123, s[40:41]
	v_cndmask_b32_e64 v164, v124, v118, s[40:41]
	v_cndmask_b32_e64 v165, v125, v119, s[40:41]
	v_cndmask_b32_e64 v166, v118, v126, s[40:41]
	v_cndmask_b32_e64 v167, v119, v127, s[40:41]
	global_store_dwordx4 v[132:133], v[160:163], off sc1
	global_store_dwordx4 v[132:133], v[164:167], off offset:1024 sc1
	v_lshl_add_u64 v[132:133], v[132:133], 0, v[154:155]
	global_load_dwordx4 v[32:35], v[128:129], off nt
	global_load_dwordx4 v[36:39], v[128:129], off offset:1024 nt
	global_load_dwordx4 v[40:43], v[128:129], off offset:2048 nt
	global_load_dwordx4 v[44:47], v[128:129], off offset:3072 nt
	v_lshl_add_u64 v[128:129], v[128:129], 0, v[152:153]
	s_cmp_lg_u32 s0, 2
	s_cbranch_scc1 .Lln1a_nopark
	v_lshl_add_u64 v[128:129], s[60:61], 0, v[148:149]
.Lln1a_nopark:
	v_add_f32_e32 v112, v0, v1
	v_add_f32_e32 v113, v2, v3
	v_add_f32_e32 v114, v4, v5
	v_add_f32_e32 v115, v6, v7
	v_add_f32_e32 v116, v8, v9
	v_add_f32_e32 v117, v10, v11
	v_add_f32_e32 v118, v12, v13
	v_add_f32_e32 v119, v14, v15
	v_add_f32_e32 v112, v112, v116
	v_add_f32_e32 v113, v113, v117
	v_add_f32_e32 v114, v114, v118
	v_add_f32_e32 v115, v115, v119
	v_add_f32_e32 v112, v112, v113
	v_add_f32_e32 v114, v114, v115
	v_add_f32_e32 v112, v112, v114
	s_nop 1
	v_add_f32_dpp v112, v112, v112 quad_perm:[1,0,3,2] row_mask:0xf bank_mask:0xf
	s_nop 1
	v_add_f32_dpp v112, v112, v112 quad_perm:[2,3,0,1] row_mask:0xf bank_mask:0xf
	s_nop 1
	v_add_f32_dpp v112, v112, v112 row_half_mirror row_mask:0xf bank_mask:0xf
	s_nop 1
	v_add_f32_dpp v112, v112, v112 row_mirror row_mask:0xf bank_mask:0xf
	s_nop 1
	v_add_f32_dpp v112, v112, v112 row_bcast:15 row_mask:0xa bank_mask:0xf
	s_nop 1
	v_add_f32_dpp v112, v112, v112 row_bcast:31 row_mask:0xc bank_mask:0xf
	s_nop 1
	v_readlane_b32 s2, v112, 63
	s_nop 1
	v_fmac_f32_e32 v0, s2, v142
	v_fmac_f32_e32 v1, s2, v142
	v_fmac_f32_e32 v2, s2, v142
	v_fmac_f32_e32 v3, s2, v142
	v_fmac_f32_e32 v4, s2, v142
	v_fmac_f32_e32 v5, s2, v142
	v_fmac_f32_e32 v6, s2, v142
	v_fmac_f32_e32 v7, s2, v142
	v_fmac_f32_e32 v8, s2, v142
	v_fmac_f32_e32 v9, s2, v142
	v_fmac_f32_e32 v10, s2, v142
	v_fmac_f32_e32 v11, s2, v142
	v_fmac_f32_e32 v12, s2, v142
	v_fmac_f32_e32 v13, s2, v142
	v_fmac_f32_e32 v14, s2, v142
	v_fmac_f32_e32 v15, s2, v142
	v_mul_f32_e32 v112, v0, v0
	v_mul_f32_e32 v113, v1, v1
	v_mul_f32_e32 v114, v2, v2
	v_mul_f32_e32 v115, v3, v3
	v_fmac_f32_e32 v112, v4, v4
	v_fmac_f32_e32 v113, v5, v5
	v_fmac_f32_e32 v114, v6, v6
	v_fmac_f32_e32 v115, v7, v7
	v_fmac_f32_e32 v112, v8, v8
	v_fmac_f32_e32 v113, v9, v9
	v_fmac_f32_e32 v114, v10, v10
	v_fmac_f32_e32 v115, v11, v11
	v_fmac_f32_e32 v112, v12, v12
	v_fmac_f32_e32 v113, v13, v13
	v_fmac_f32_e32 v114, v14, v14
	v_fmac_f32_e32 v115, v15, v15
	v_add_f32_e32 v112, v112, v113
	v_add_f32_e32 v114, v114, v115
	v_add_f32_e32 v112, v112, v114
	s_nop 1
	v_add_f32_dpp v112, v112, v112 quad_perm:[1,0,3,2] row_mask:0xf bank_mask:0xf
	s_nop 1
	v_add_f32_dpp v112, v112, v112 quad_perm:[2,3,0,1] row_mask:0xf bank_mask:0xf
	s_nop 1
	v_add_f32_dpp v112, v112, v112 row_half_mirror row_mask:0xf bank_mask:0xf
	s_nop 1
	v_add_f32_dpp v112, v112, v112 row_mirror row_mask:0xf bank_mask:0xf
	s_nop 1
	v_add_f32_dpp v112, v112, v112 row_bcast:15 row_mask:0xa bank_mask:0xf
	s_nop 1
	v_add_f32_dpp v112, v112, v112 row_bcast:31 row_mask:0xc bank_mask:0xf
	s_nop 1
	v_readlane_b32 s2, v112, 63
	s_nop 1
	v_mov_b32_e32 v113, 0x358637bd
	v_mov_b32_e32 v114, 0x3a800000
	v_fmac_f32_e32 v113, s2, v114
	v_rsq_f32_e32 v115, v113
	v_mul_f32_e32 v113, 0.5, v113
	v_mul_f32_e32 v116, v115, v115
	v_mov_b32_e32 v117, 0x3fc00000
	v_fma_f32 v116, -v113, v116, v117
	v_mul_f32_e32 v144, v115, v116
	v_pk_mul_f32 v[0:1], v[0:1], v[144:145] op_sel_hi:[1,0]
	v_pk_mul_f32 v[2:3], v[2:3], v[144:145] op_sel_hi:[1,0]
	v_pk_mul_f32 v[4:5], v[4:5], v[144:145] op_sel_hi:[1,0]
	v_pk_mul_f32 v[6:7], v[6:7], v[144:145] op_sel_hi:[1,0]
	v_pk_mul_f32 v[8:9], v[8:9], v[144:145] op_sel_hi:[1,0]
	v_pk_mul_f32 v[10:11], v[10:11], v[144:145] op_sel_hi:[1,0]
	v_pk_mul_f32 v[12:13], v[12:13], v[144:145] op_sel_hi:[1,0]
	v_pk_mul_f32 v[14:15], v[14:15], v[144:145] op_sel_hi:[1,0]
	v_pk_fma_f32 v[0:1], v[80:81], v[0:1], v[96:97]
	v_pk_fma_f32 v[2:3], v[82:83], v[2:3], v[98:99]
	v_pk_fma_f32 v[4:5], v[84:85], v[4:5], v[100:101]
	v_pk_fma_f32 v[6:7], v[86:87], v[6:7], v[102:103]
	v_pk_fma_f32 v[8:9], v[88:89], v[8:9], v[104:105]
	v_pk_fma_f32 v[10:11], v[90:91], v[10:11], v[106:107]
	v_pk_fma_f32 v[12:13], v[92:93], v[12:13], v[108:109]
	v_pk_fma_f32 v[14:15], v[94:95], v[14:15], v[110:111]
	global_store_dwordx4 v[130:131], v[0:3], off sc1
	global_store_dwordx4 v[130:131], v[4:7], off offset:1024 sc1
	global_store_dwordx4 v[130:131], v[8:11], off offset:2048 sc1
	global_store_dwordx4 v[130:131], v[12:15], off offset:3072 sc1
	v_lshl_add_u64 v[130:131], v[130:131], 0, v[152:153]
	v_add_f32_e32 v112, v0, v1
	v_add_f32_e32 v113, v2, v3
	v_add_f32_e32 v114, v4, v5
	v_add_f32_e32 v115, v6, v7
	v_add_f32_e32 v116, v8, v9
	v_add_f32_e32 v117, v10, v11
	v_add_f32_e32 v118, v12, v13
	v_add_f32_e32 v119, v14, v15
	v_add_f32_e32 v112, v112, v116
	v_add_f32_e32 v113, v113, v117
	v_add_f32_e32 v114, v114, v118
	v_add_f32_e32 v115, v115, v119
	v_add_f32_e32 v112, v112, v113
	v_add_f32_e32 v114, v114, v115
	v_add_f32_e32 v112, v112, v114
	s_nop 1
	v_add_f32_dpp v112, v112, v112 quad_perm:[1,0,3,2] row_mask:0xf bank_mask:0xf
	s_nop 1
	v_add_f32_dpp v112, v112, v112 quad_perm:[2,3,0,1] row_mask:0xf bank_mask:0xf
	s_nop 1
	v_add_f32_dpp v112, v112, v112 row_half_mirror row_mask:0xf bank_mask:0xf
	s_nop 1
	v_add_f32_dpp v112, v112, v112 row_mirror row_mask:0xf bank_mask:0xf
	s_nop 1
	v_add_f32_dpp v112, v112, v112 row_bcast:15 row_mask:0xa bank_mask:0xf
	s_nop 1
	v_add_f32_dpp v112, v112, v112 row_bcast:31 row_mask:0xc bank_mask:0xf
	s_nop 1
	v_readlane_b32 s2, v112, 63
	s_nop 1
	v_fmac_f32_e32 v0, s2, v142
	v_fmac_f32_e32 v1, s2, v142
	v_fmac_f32_e32 v2, s2, v142
	v_fmac_f32_e32 v3, s2, v142
	v_fmac_f32_e32 v4, s2, v142
	v_fmac_f32_e32 v5, s2, v142
	v_fmac_f32_e32 v6, s2, v142
	v_fmac_f32_e32 v7, s2, v142
	v_fmac_f32_e32 v8, s2, v142
	v_fmac_f32_e32 v9, s2, v142
	v_fmac_f32_e32 v10, s2, v142
	v_fmac_f32_e32 v11, s2, v142
	v_fmac_f32_e32 v12, s2, v142
	v_fmac_f32_e32 v13, s2, v142
	v_fmac_f32_e32 v14, s2, v142
	v_fmac_f32_e32 v15, s2, v142
	v_mul_f32_e32 v112, v0, v0
	v_mul_f32_e32 v113, v1, v1
	v_mul_f32_e32 v114, v2, v2
	v_mul_f32_e32 v115, v3, v3
	v_fmac_f32_e32 v112, v4, v4
	v_fmac_f32_e32 v113, v5, v5
	v_fmac_f32_e32 v114, v6, v6
	v_fmac_f32_e32 v115, v7, v7
	v_fmac_f32_e32 v112, v8, v8
	v_fmac_f32_e32 v113, v9, v9
	v_fmac_f32_e32 v114, v10, v10
	v_fmac_f32_e32 v115, v11, v11
	v_fmac_f32_e32 v112, v12, v12
	v_fmac_f32_e32 v113, v13, v13
	v_fmac_f32_e32 v114, v14, v14
	v_fmac_f32_e32 v115, v15, v15
	v_add_f32_e32 v112, v112, v113
	v_add_f32_e32 v114, v114, v115
	v_add_f32_e32 v112, v112, v114
	s_nop 1
	v_add_f32_dpp v112, v112, v112 quad_perm:[1,0,3,2] row_mask:0xf bank_mask:0xf
	s_nop 1
	v_add_f32_dpp v112, v112, v112 quad_perm:[2,3,0,1] row_mask:0xf bank_mask:0xf
	s_nop 1
	v_add_f32_dpp v112, v112, v112 row_half_mirror row_mask:0xf bank_mask:0xf
	s_nop 1
	v_add_f32_dpp v112, v112, v112 row_mirror row_mask:0xf bank_mask:0xf
	s_nop 1
	v_add_f32_dpp v112, v112, v112 row_bcast:15 row_mask:0xa bank_mask:0xf
	s_nop 1
	v_add_f32_dpp v112, v112, v112 row_bcast:31 row_mask:0xc bank_mask:0xf
	s_nop 1
	v_readlane_b32 s2, v112, 63
	s_nop 1
	v_mov_b32_e32 v113, 0x358637bd
	v_mov_b32_e32 v114, 0x3a800000
	v_fmac_f32_e32 v113, s2, v114
	v_rsq_f32_e32 v115, v113
	v_mul_f32_e32 v113, 0.5, v113
	v_mul_f32_e32 v116, v115, v115
	v_mov_b32_e32 v117, 0x3fc00000
	v_fma_f32 v116, -v113, v116, v117
	v_mul_f32_e32 v144, v115, v116
	v_pk_mul_f32 v[0:1], v[0:1], v[144:145] op_sel_hi:[1,0]
	v_pk_mul_f32 v[2:3], v[2:3], v[144:145] op_sel_hi:[1,0]
	v_pk_mul_f32 v[4:5], v[4:5], v[144:145] op_sel_hi:[1,0]
	v_pk_mul_f32 v[6:7], v[6:7], v[144:145] op_sel_hi:[1,0]
	v_pk_mul_f32 v[8:9], v[8:9], v[144:145] op_sel_hi:[1,0]
	v_pk_mul_f32 v[10:11], v[10:11], v[144:145] op_sel_hi:[1,0]
	v_pk_mul_f32 v[12:13], v[12:13], v[144:145] op_sel_hi:[1,0]
	v_pk_mul_f32 v[14:15], v[14:15], v[144:145] op_sel_hi:[1,0]
	v_pk_fma_f32 v[0:1], v[64:65], v[0:1], v[48:49]
	v_pk_fma_f32 v[2:3], v[66:67], v[2:3], v[50:51]
	v_pk_fma_f32 v[4:5], v[68:69], v[4:5], v[52:53]
	v_pk_fma_f32 v[6:7], v[70:71], v[6:7], v[54:55]
	v_pk_fma_f32 v[8:9], v[72:73], v[8:9], v[56:57]
	v_pk_fma_f32 v[10:11], v[74:75], v[10:11], v[58:59]
	v_pk_fma_f32 v[12:13], v[76:77], v[12:13], v[60:61]
	v_pk_fma_f32 v[14:15], v[78:79], v[14:15], v[62:63]
	v_cvt_pk_bf16_f32 v120, v0, v1
	v_cvt_pk_bf16_f32 v121, v2, v3
	v_cvt_pk_bf16_f32 v122, v4, v5
	v_cvt_pk_bf16_f32 v123, v6, v7
	v_cvt_pk_bf16_f32 v124, v8, v9
	v_cvt_pk_bf16_f32 v125, v10, v11
	v_cvt_pk_bf16_f32 v126, v12, v13
	v_cvt_pk_bf16_f32 v127, v14, v15
	v_cndmask_b32_e64 v112, v122, v120, s[40:41]
	v_cndmask_b32_e64 v113, v123, v121, s[40:41]
	v_cndmask_b32_e64 v114, v126, v124, s[40:41]
	v_cndmask_b32_e64 v115, v127, v125, s[40:41]
	v_mov_b32_dpp v116, v112 quad_perm:[1,0,3,2] row_mask:0xf bank_mask:0xf
	v_mov_b32_dpp v117, v113 quad_perm:[1,0,3,2] row_mask:0xf bank_mask:0xf
	v_mov_b32_dpp v118, v114 quad_perm:[1,0,3,2] row_mask:0xf bank_mask:0xf
	v_mov_b32_dpp v119, v115 quad_perm:[1,0,3,2] row_mask:0xf bank_mask:0xf
	s_nop 0
	v_cndmask_b32_e64 v160, v120, v116, s[40:41]
	v_cndmask_b32_e64 v161, v121, v117, s[40:41]
	v_cndmask_b32_e64 v162, v116, v122, s[40:41]
	v_cndmask_b32_e64 v163, v117, v123, s[40:41]
	v_cndmask_b32_e64 v164, v124, v118, s[40:41]
	v_cndmask_b32_e64 v165, v125, v119, s[40:41]
	v_cndmask_b32_e64 v166, v118, v126, s[40:41]
	v_cndmask_b32_e64 v167, v119, v127, s[40:41]
	global_store_dwordx4 v[132:133], v[160:163], off sc1
	global_store_dwordx4 v[132:133], v[164:167], off offset:1024 sc1
	v_lshl_add_u64 v[132:133], v[132:133], 0, v[154:155]
	global_load_dwordx4 v[48:51], v[134:135], off offset:-4096
	global_load_dwordx4 v[52:55], v[134:135], off offset:-3072
	global_load_dwordx4 v[56:59], v[134:135], off offset:-2048
	global_load_dwordx4 v[60:63], v[134:135], off offset:-1024
	global_load_dwordx4 v[64:67], v[134:135], off
	global_load_dwordx4 v[68:71], v[134:135], off offset:1024
	global_load_dwordx4 v[72:75], v[134:135], off offset:2048
	global_load_dwordx4 v[76:79], v[134:135], off offset:3072
	v_lshl_add_u64 v[134:135], v[134:135], 0, v[156:157]
	global_load_dwordx4 v[0:3], v[128:129], off nt
	global_load_dwordx4 v[4:7], v[128:129], off offset:1024 nt
	global_load_dwordx4 v[8:11], v[128:129], off offset:2048 nt
	global_load_dwordx4 v[12:15], v[128:129], off offset:3072 nt
	v_lshl_add_u64 v[128:129], v[128:129], 0, v[152:153]
	s_waitcnt vmcnt(28)
	v_add_f32_e32 v112, v16, v17
	v_add_f32_e32 v113, v18, v19
	v_add_f32_e32 v114, v20, v21
	v_add_f32_e32 v115, v22, v23
	v_add_f32_e32 v116, v24, v25
	v_add_f32_e32 v117, v26, v27
	v_add_f32_e32 v118, v28, v29
	v_add_f32_e32 v119, v30, v31
	v_add_f32_e32 v112, v112, v116
	v_add_f32_e32 v113, v113, v117
	v_add_f32_e32 v114, v114, v118
	v_add_f32_e32 v115, v115, v119
	v_add_f32_e32 v112, v112, v113
	v_add_f32_e32 v114, v114, v115
	v_add_f32_e32 v112, v112, v114
	s_nop 1
	v_add_f32_dpp v112, v112, v112 quad_perm:[1,0,3,2] row_mask:0xf bank_mask:0xf
	s_nop 1
	v_add_f32_dpp v112, v112, v112 quad_perm:[2,3,0,1] row_mask:0xf bank_mask:0xf
	s_nop 1
	v_add_f32_dpp v112, v112, v112 row_half_mirror row_mask:0xf bank_mask:0xf
	s_nop 1
	v_add_f32_dpp v112, v112, v112 row_mirror row_mask:0xf bank_mask:0xf
	s_nop 1
	v_add_f32_dpp v112, v112, v112 row_bcast:15 row_mask:0xa bank_mask:0xf
	s_nop 1
	v_add_f32_dpp v112, v112, v112 row_bcast:31 row_mask:0xc bank_mask:0xf
	s_nop 1
	v_readlane_b32 s2, v112, 63
	s_nop 1
	v_fmac_f32_e32 v16, s2, v142
	v_fmac_f32_e32 v17, s2, v142
	v_fmac_f32_e32 v18, s2, v142
	v_fmac_f32_e32 v19, s2, v142
	v_fmac_f32_e32 v20, s2, v142
	v_fmac_f32_e32 v21, s2, v142
	v_fmac_f32_e32 v22, s2, v142
	v_fmac_f32_e32 v23, s2, v142
	v_fmac_f32_e32 v24, s2, v142
	v_fmac_f32_e32 v25, s2, v142
	v_fmac_f32_e32 v26, s2, v142
	v_fmac_f32_e32 v27, s2, v142
	v_fmac_f32_e32 v28, s2, v142
	v_fmac_f32_e32 v29, s2, v142
	v_fmac_f32_e32 v30, s2, v142
	v_fmac_f32_e32 v31, s2, v142
	v_mul_f32_e32 v112, v16, v16
	v_mul_f32_e32 v113, v17, v17
	v_mul_f32_e32 v114, v18, v18
	v_mul_f32_e32 v115, v19, v19
	v_fmac_f32_e32 v112, v20, v20
	v_fmac_f32_e32 v113, v21, v21
	v_fmac_f32_e32 v114, v22, v22
	v_fmac_f32_e32 v115, v23, v23
	v_fmac_f32_e32 v112, v24, v24
	v_fmac_f32_e32 v113, v25, v25
	v_fmac_f32_e32 v114, v26, v26
	v_fmac_f32_e32 v115, v27, v27
	v_fmac_f32_e32 v112, v28, v28
	v_fmac_f32_e32 v113, v29, v29
	v_fmac_f32_e32 v114, v30, v30
	v_fmac_f32_e32 v115, v31, v31
	v_add_f32_e32 v112, v112, v113
	v_add_f32_e32 v114, v114, v115
	v_add_f32_e32 v112, v112, v114
	s_nop 1
	v_add_f32_dpp v112, v112, v112 quad_perm:[1,0,3,2] row_mask:0xf bank_mask:0xf
	s_nop 1
	v_add_f32_dpp v112, v112, v112 quad_perm:[2,3,0,1] row_mask:0xf bank_mask:0xf
	s_nop 1
	v_add_f32_dpp v112, v112, v112 row_half_mirror row_mask:0xf bank_mask:0xf
	s_nop 1
	v_add_f32_dpp v112, v112, v112 row_mirror row_mask:0xf bank_mask:0xf
	s_nop 1
	v_add_f32_dpp v112, v112, v112 row_bcast:15 row_mask:0xa bank_mask:0xf
	s_nop 1
	v_add_f32_dpp v112, v112, v112 row_bcast:31 row_mask:0xc bank_mask:0xf
	s_nop 1
	v_readlane_b32 s2, v112, 63
	s_nop 1
	v_mov_b32_e32 v113, 0x358637bd
	v_mov_b32_e32 v114, 0x3a800000
	v_fmac_f32_e32 v113, s2, v114
	v_rsq_f32_e32 v115, v113
	v_mul_f32_e32 v113, 0.5, v113
	v_mul_f32_e32 v116, v115, v115
	v_mov_b32_e32 v117, 0x3fc00000
	v_fma_f32 v116, -v113, v116, v117
	v_mul_f32_e32 v144, v115, v116
	v_pk_mul_f32 v[16:17], v[16:17], v[144:145] op_sel_hi:[1,0]
	v_pk_mul_f32 v[18:19], v[18:19], v[144:145] op_sel_hi:[1,0]
	v_pk_mul_f32 v[20:21], v[20:21], v[144:145] op_sel_hi:[1,0]
	v_pk_mul_f32 v[22:23], v[22:23], v[144:145] op_sel_hi:[1,0]
	v_pk_mul_f32 v[24:25], v[24:25], v[144:145] op_sel_hi:[1,0]
	v_pk_mul_f32 v[26:27], v[26:27], v[144:145] op_sel_hi:[1,0]
	v_pk_mul_f32 v[28:29], v[28:29], v[144:145] op_sel_hi:[1,0]
	v_pk_mul_f32 v[30:31], v[30:31], v[144:145] op_sel_hi:[1,0]
	v_pk_fma_f32 v[16:17], v[80:81], v[16:17], v[96:97]
	v_pk_fma_f32 v[18:19], v[82:83], v[18:19], v[98:99]
	v_pk_fma_f32 v[20:21], v[84:85], v[20:21], v[100:101]
	v_pk_fma_f32 v[22:23], v[86:87], v[22:23], v[102:103]
	v_pk_fma_f32 v[24:25], v[88:89], v[24:25], v[104:105]
	v_pk_fma_f32 v[26:27], v[90:91], v[26:27], v[106:107]
	v_pk_fma_f32 v[28:29], v[92:93], v[28:29], v[108:109]
	v_pk_fma_f32 v[30:31], v[94:95], v[30:31], v[110:111]
	global_store_dwordx4 v[130:131], v[16:19], off sc1
	global_store_dwordx4 v[130:131], v[20:23], off offset:1024 sc1
	global_store_dwordx4 v[130:131], v[24:27], off offset:2048 sc1
	global_store_dwordx4 v[130:131], v[28:31], off offset:3072 sc1
	v_lshl_add_u64 v[130:131], v[130:131], 0, v[152:153]
	v_add_f32_e32 v112, v16, v17
	v_add_f32_e32 v113, v18, v19
	v_add_f32_e32 v114, v20, v21
	v_add_f32_e32 v115, v22, v23
	v_add_f32_e32 v116, v24, v25
	v_add_f32_e32 v117, v26, v27
	v_add_f32_e32 v118, v28, v29
	v_add_f32_e32 v119, v30, v31
	v_add_f32_e32 v112, v112, v116
	v_add_f32_e32 v113, v113, v117
	v_add_f32_e32 v114, v114, v118
	v_add_f32_e32 v115, v115, v119
	v_add_f32_e32 v112, v112, v113
	v_add_f32_e32 v114, v114, v115
	v_add_f32_e32 v112, v112, v114
	s_nop 1
	v_add_f32_dpp v112, v112, v112 quad_perm:[1,0,3,2] row_mask:0xf bank_mask:0xf
	s_nop 1
	v_add_f32_dpp v112, v112, v112 quad_perm:[2,3,0,1] row_mask:0xf bank_mask:0xf
	s_nop 1
	v_add_f32_dpp v112, v112, v112 row_half_mirror row_mask:0xf bank_mask:0xf
	s_nop 1
	v_add_f32_dpp v112, v112, v112 row_mirror row_mask:0xf bank_mask:0xf
	s_nop 1
	v_add_f32_dpp v112, v112, v112 row_bcast:15 row_mask:0xa bank_mask:0xf
	s_nop 1
	v_add_f32_dpp v112, v112, v112 row_bcast:31 row_mask:0xc bank_mask:0xf
	s_nop 1
	v_readlane_b32 s2, v112, 63
	s_nop 1
	v_fmac_f32_e32 v16, s2, v142
	v_fmac_f32_e32 v17, s2, v142
	v_fmac_f32_e32 v18, s2, v142
	v_fmac_f32_e32 v19, s2, v142
	v_fmac_f32_e32 v20, s2, v142
	v_fmac_f32_e32 v21, s2, v142
	v_fmac_f32_e32 v22, s2, v142
	v_fmac_f32_e32 v23, s2, v142
	v_fmac_f32_e32 v24, s2, v142
	v_fmac_f32_e32 v25, s2, v142
	v_fmac_f32_e32 v26, s2, v142
	v_fmac_f32_e32 v27, s2, v142
	v_fmac_f32_e32 v28, s2, v142
	v_fmac_f32_e32 v29, s2, v142
	v_fmac_f32_e32 v30, s2, v142
	v_fmac_f32_e32 v31, s2, v142
	v_mul_f32_e32 v112, v16, v16
	v_mul_f32_e32 v113, v17, v17
	v_mul_f32_e32 v114, v18, v18
	v_mul_f32_e32 v115, v19, v19
	v_fmac_f32_e32 v112, v20, v20
	v_fmac_f32_e32 v113, v21, v21
	v_fmac_f32_e32 v114, v22, v22
	v_fmac_f32_e32 v115, v23, v23
	v_fmac_f32_e32 v112, v24, v24
	v_fmac_f32_e32 v113, v25, v25
	v_fmac_f32_e32 v114, v26, v26
	v_fmac_f32_e32 v115, v27, v27
	v_fmac_f32_e32 v112, v28, v28
	v_fmac_f32_e32 v113, v29, v29
	v_fmac_f32_e32 v114, v30, v30
	v_fmac_f32_e32 v115, v31, v31
	v_add_f32_e32 v112, v112, v113
	v_add_f32_e32 v114, v114, v115
	v_add_f32_e32 v112, v112, v114
	s_nop 1
	v_add_f32_dpp v112, v112, v112 quad_perm:[1,0,3,2] row_mask:0xf bank_mask:0xf
	s_nop 1
	v_add_f32_dpp v112, v112, v112 quad_perm:[2,3,0,1] row_mask:0xf bank_mask:0xf
	s_nop 1
	v_add_f32_dpp v112, v112, v112 row_half_mirror row_mask:0xf bank_mask:0xf
	s_nop 1
	v_add_f32_dpp v112, v112, v112 row_mirror row_mask:0xf bank_mask:0xf
	s_nop 1
	v_add_f32_dpp v112, v112, v112 row_bcast:15 row_mask:0xa bank_mask:0xf
	s_nop 1
	v_add_f32_dpp v112, v112, v112 row_bcast:31 row_mask:0xc bank_mask:0xf
	s_nop 1
	v_readlane_b32 s2, v112, 63
	s_nop 1
	v_mov_b32_e32 v113, 0x358637bd
	v_mov_b32_e32 v114, 0x3a800000
	v_fmac_f32_e32 v113, s2, v114
	v_rsq_f32_e32 v115, v113
	v_mul_f32_e32 v113, 0.5, v113
	v_mul_f32_e32 v116, v115, v115
	v_mov_b32_e32 v117, 0x3fc00000
	v_fma_f32 v116, -v113, v116, v117
	v_mul_f32_e32 v144, v115, v116
	v_pk_mul_f32 v[16:17], v[16:17], v[144:145] op_sel_hi:[1,0]
	v_pk_mul_f32 v[18:19], v[18:19], v[144:145] op_sel_hi:[1,0]
	v_pk_mul_f32 v[20:21], v[20:21], v[144:145] op_sel_hi:[1,0]
	v_pk_mul_f32 v[22:23], v[22:23], v[144:145] op_sel_hi:[1,0]
	v_pk_mul_f32 v[24:25], v[24:25], v[144:145] op_sel_hi:[1,0]
	v_pk_mul_f32 v[26:27], v[26:27], v[144:145] op_sel_hi:[1,0]
	v_pk_mul_f32 v[28:29], v[28:29], v[144:145] op_sel_hi:[1,0]
	v_pk_mul_f32 v[30:31], v[30:31], v[144:145] op_sel_hi:[1,0]
	s_waitcnt vmcnt(8)
	v_pk_add_f32 v[64:65], v[64:65], 1.0 op_sel_hi:[1,0]
	v_pk_add_f32 v[66:67], v[66:67], 1.0 op_sel_hi:[1,0]
	v_pk_add_f32 v[68:69], v[68:69], 1.0 op_sel_hi:[1,0]
	v_pk_add_f32 v[70:71], v[70:71], 1.0 op_sel_hi:[1,0]
	v_pk_add_f32 v[72:73], v[72:73], 1.0 op_sel_hi:[1,0]
	v_pk_add_f32 v[74:75], v[74:75], 1.0 op_sel_hi:[1,0]
	v_pk_add_f32 v[76:77], v[76:77], 1.0 op_sel_hi:[1,0]
	v_pk_add_f32 v[78:79], v[78:79], 1.0 op_sel_hi:[1,0]
	v_pk_fma_f32 v[16:17], v[64:65], v[16:17], v[48:49]
	v_pk_fma_f32 v[18:19], v[66:67], v[18:19], v[50:51]
	v_pk_fma_f32 v[20:21], v[68:69], v[20:21], v[52:53]
	v_pk_fma_f32 v[22:23], v[70:71], v[22:23], v[54:55]
	v_pk_fma_f32 v[24:25], v[72:73], v[24:25], v[56:57]
	v_pk_fma_f32 v[26:27], v[74:75], v[26:27], v[58:59]
	v_pk_fma_f32 v[28:29], v[76:77], v[28:29], v[60:61]
	v_pk_fma_f32 v[30:31], v[78:79], v[30:31], v[62:63]
	v_cvt_pk_bf16_f32 v120, v16, v17
	v_cvt_pk_bf16_f32 v121, v18, v19
	v_cvt_pk_bf16_f32 v122, v20, v21
	v_cvt_pk_bf16_f32 v123, v22, v23
	v_cvt_pk_bf16_f32 v124, v24, v25
	v_cvt_pk_bf16_f32 v125, v26, v27
	v_cvt_pk_bf16_f32 v126, v28, v29
	v_cvt_pk_bf16_f32 v127, v30, v31
	v_cndmask_b32_e64 v112, v122, v120, s[40:41]
	v_cndmask_b32_e64 v113, v123, v121, s[40:41]
	v_cndmask_b32_e64 v114, v126, v124, s[40:41]
	v_cndmask_b32_e64 v115, v127, v125, s[40:41]
	v_mov_b32_dpp v116, v112 quad_perm:[1,0,3,2] row_mask:0xf bank_mask:0xf
	v_mov_b32_dpp v117, v113 quad_perm:[1,0,3,2] row_mask:0xf bank_mask:0xf
	v_mov_b32_dpp v118, v114 quad_perm:[1,0,3,2] row_mask:0xf bank_mask:0xf
	v_mov_b32_dpp v119, v115 quad_perm:[1,0,3,2] row_mask:0xf bank_mask:0xf
	s_nop 0
	v_cndmask_b32_e64 v160, v120, v116, s[40:41]
	v_cndmask_b32_e64 v161, v121, v117, s[40:41]
	v_cndmask_b32_e64 v162, v116, v122, s[40:41]
	v_cndmask_b32_e64 v163, v117, v123, s[40:41]
	v_cndmask_b32_e64 v164, v124, v118, s[40:41]
	v_cndmask_b32_e64 v165, v125, v119, s[40:41]
	v_cndmask_b32_e64 v166, v118, v126, s[40:41]
	v_cndmask_b32_e64 v167, v119, v127, s[40:41]
	global_store_dwordx4 v[132:133], v[160:163], off sc1
	global_store_dwordx4 v[132:133], v[164:167], off offset:1024 sc1
	v_lshl_add_u64 v[132:133], v[132:133], 0, v[154:155]
	global_load_dwordx4 v[16:19], v[128:129], off nt
	global_load_dwordx4 v[20:23], v[128:129], off offset:1024 nt
	global_load_dwordx4 v[24:27], v[128:129], off offset:2048 nt
	global_load_dwordx4 v[28:31], v[128:129], off offset:3072 nt
	v_lshl_add_u64 v[128:129], v[128:129], 0, v[152:153]
	v_add_f32_e32 v112, v32, v33
	v_add_f32_e32 v113, v34, v35
	v_add_f32_e32 v114, v36, v37
	v_add_f32_e32 v115, v38, v39
	v_add_f32_e32 v116, v40, v41
	v_add_f32_e32 v117, v42, v43
	v_add_f32_e32 v118, v44, v45
	v_add_f32_e32 v119, v46, v47
	v_add_f32_e32 v112, v112, v116
	v_add_f32_e32 v113, v113, v117
	v_add_f32_e32 v114, v114, v118
	v_add_f32_e32 v115, v115, v119
	v_add_f32_e32 v112, v112, v113
	v_add_f32_e32 v114, v114, v115
	v_add_f32_e32 v112, v112, v114
	s_nop 1
	v_add_f32_dpp v112, v112, v112 quad_perm:[1,0,3,2] row_mask:0xf bank_mask:0xf
	s_nop 1
	v_add_f32_dpp v112, v112, v112 quad_perm:[2,3,0,1] row_mask:0xf bank_mask:0xf
	s_nop 1
	v_add_f32_dpp v112, v112, v112 row_half_mirror row_mask:0xf bank_mask:0xf
	s_nop 1
	v_add_f32_dpp v112, v112, v112 row_mirror row_mask:0xf bank_mask:0xf
	s_nop 1
	v_add_f32_dpp v112, v112, v112 row_bcast:15 row_mask:0xa bank_mask:0xf
	s_nop 1
	v_add_f32_dpp v112, v112, v112 row_bcast:31 row_mask:0xc bank_mask:0xf
	s_nop 1
	v_readlane_b32 s2, v112, 63
	s_nop 1
	v_fmac_f32_e32 v32, s2, v142
	v_fmac_f32_e32 v33, s2, v142
	v_fmac_f32_e32 v34, s2, v142
	v_fmac_f32_e32 v35, s2, v142
	v_fmac_f32_e32 v36, s2, v142
	v_fmac_f32_e32 v37, s2, v142
	v_fmac_f32_e32 v38, s2, v142
	v_fmac_f32_e32 v39, s2, v142
	v_fmac_f32_e32 v40, s2, v142
	v_fmac_f32_e32 v41, s2, v142
	v_fmac_f32_e32 v42, s2, v142
	v_fmac_f32_e32 v43, s2, v142
	v_fmac_f32_e32 v44, s2, v142
	v_fmac_f32_e32 v45, s2, v142
	v_fmac_f32_e32 v46, s2, v142
	v_fmac_f32_e32 v47, s2, v142
	v_mul_f32_e32 v112, v32, v32
	v_mul_f32_e32 v113, v33, v33
	v_mul_f32_e32 v114, v34, v34
	v_mul_f32_e32 v115, v35, v35
	v_fmac_f32_e32 v112, v36, v36
	v_fmac_f32_e32 v113, v37, v37
	v_fmac_f32_e32 v114, v38, v38
	v_fmac_f32_e32 v115, v39, v39
	v_fmac_f32_e32 v112, v40, v40
	v_fmac_f32_e32 v113, v41, v41
	v_fmac_f32_e32 v114, v42, v42
	v_fmac_f32_e32 v115, v43, v43
	v_fmac_f32_e32 v112, v44, v44
	v_fmac_f32_e32 v113, v45, v45
	v_fmac_f32_e32 v114, v46, v46
	v_fmac_f32_e32 v115, v47, v47
	v_add_f32_e32 v112, v112, v113
	v_add_f32_e32 v114, v114, v115
	v_add_f32_e32 v112, v112, v114
	s_nop 1
	v_add_f32_dpp v112, v112, v112 quad_perm:[1,0,3,2] row_mask:0xf bank_mask:0xf
	s_nop 1
	v_add_f32_dpp v112, v112, v112 quad_perm:[2,3,0,1] row_mask:0xf bank_mask:0xf
	s_nop 1
	v_add_f32_dpp v112, v112, v112 row_half_mirror row_mask:0xf bank_mask:0xf
	s_nop 1
	v_add_f32_dpp v112, v112, v112 row_mirror row_mask:0xf bank_mask:0xf
	s_nop 1
	v_add_f32_dpp v112, v112, v112 row_bcast:15 row_mask:0xa bank_mask:0xf
	s_nop 1
	v_add_f32_dpp v112, v112, v112 row_bcast:31 row_mask:0xc bank_mask:0xf
	s_nop 1
	v_readlane_b32 s2, v112, 63
	s_nop 1
	v_mov_b32_e32 v113, 0x358637bd
	v_mov_b32_e32 v114, 0x3a800000
	v_fmac_f32_e32 v113, s2, v114
	v_rsq_f32_e32 v115, v113
	v_mul_f32_e32 v113, 0.5, v113
	v_mul_f32_e32 v116, v115, v115
	v_mov_b32_e32 v117, 0x3fc00000
	v_fma_f32 v116, -v113, v116, v117
	v_mul_f32_e32 v144, v115, v116
	v_pk_mul_f32 v[32:33], v[32:33], v[144:145] op_sel_hi:[1,0]
	v_pk_mul_f32 v[34:35], v[34:35], v[144:145] op_sel_hi:[1,0]
	v_pk_mul_f32 v[36:37], v[36:37], v[144:145] op_sel_hi:[1,0]
	v_pk_mul_f32 v[38:39], v[38:39], v[144:145] op_sel_hi:[1,0]
	v_pk_mul_f32 v[40:41], v[40:41], v[144:145] op_sel_hi:[1,0]
	v_pk_mul_f32 v[42:43], v[42:43], v[144:145] op_sel_hi:[1,0]
	v_pk_mul_f32 v[44:45], v[44:45], v[144:145] op_sel_hi:[1,0]
	v_pk_mul_f32 v[46:47], v[46:47], v[144:145] op_sel_hi:[1,0]
	v_pk_fma_f32 v[32:33], v[80:81], v[32:33], v[96:97]
	v_pk_fma_f32 v[34:35], v[82:83], v[34:35], v[98:99]
	v_pk_fma_f32 v[36:37], v[84:85], v[36:37], v[100:101]
	v_pk_fma_f32 v[38:39], v[86:87], v[38:39], v[102:103]
	v_pk_fma_f32 v[40:41], v[88:89], v[40:41], v[104:105]
	v_pk_fma_f32 v[42:43], v[90:91], v[42:43], v[106:107]
	v_pk_fma_f32 v[44:45], v[92:93], v[44:45], v[108:109]
	v_pk_fma_f32 v[46:47], v[94:95], v[46:47], v[110:111]
	global_store_dwordx4 v[130:131], v[32:35], off sc1
	global_store_dwordx4 v[130:131], v[36:39], off offset:1024 sc1
	global_store_dwordx4 v[130:131], v[40:43], off offset:2048 sc1
	global_store_dwordx4 v[130:131], v[44:47], off offset:3072 sc1
	v_lshl_add_u64 v[130:131], v[130:131], 0, v[152:153]
	v_add_f32_e32 v112, v32, v33
	v_add_f32_e32 v113, v34, v35
	v_add_f32_e32 v114, v36, v37
	v_add_f32_e32 v115, v38, v39
	v_add_f32_e32 v116, v40, v41
	v_add_f32_e32 v117, v42, v43
	v_add_f32_e32 v118, v44, v45
	v_add_f32_e32 v119, v46, v47
	v_add_f32_e32 v112, v112, v116
	v_add_f32_e32 v113, v113, v117
	v_add_f32_e32 v114, v114, v118
	v_add_f32_e32 v115, v115, v119
	v_add_f32_e32 v112, v112, v113
	v_add_f32_e32 v114, v114, v115
	v_add_f32_e32 v112, v112, v114
	s_nop 1
	v_add_f32_dpp v112, v112, v112 quad_perm:[1,0,3,2] row_mask:0xf bank_mask:0xf
	s_nop 1
	v_add_f32_dpp v112, v112, v112 quad_perm:[2,3,0,1] row_mask:0xf bank_mask:0xf
	s_nop 1
	v_add_f32_dpp v112, v112, v112 row_half_mirror row_mask:0xf bank_mask:0xf
	s_nop 1
	v_add_f32_dpp v112, v112, v112 row_mirror row_mask:0xf bank_mask:0xf
	s_nop 1
	v_add_f32_dpp v112, v112, v112 row_bcast:15 row_mask:0xa bank_mask:0xf
	s_nop 1
	v_add_f32_dpp v112, v112, v112 row_bcast:31 row_mask:0xc bank_mask:0xf
	s_nop 1
	v_readlane_b32 s2, v112, 63
	s_nop 1
	v_fmac_f32_e32 v32, s2, v142
	v_fmac_f32_e32 v33, s2, v142
	v_fmac_f32_e32 v34, s2, v142
	v_fmac_f32_e32 v35, s2, v142
	v_fmac_f32_e32 v36, s2, v142
	v_fmac_f32_e32 v37, s2, v142
	v_fmac_f32_e32 v38, s2, v142
	v_fmac_f32_e32 v39, s2, v142
	v_fmac_f32_e32 v40, s2, v142
	v_fmac_f32_e32 v41, s2, v142
	v_fmac_f32_e32 v42, s2, v142
	v_fmac_f32_e32 v43, s2, v142
	v_fmac_f32_e32 v44, s2, v142
	v_fmac_f32_e32 v45, s2, v142
	v_fmac_f32_e32 v46, s2, v142
	v_fmac_f32_e32 v47, s2, v142
	v_mul_f32_e32 v112, v32, v32
	v_mul_f32_e32 v113, v33, v33
	v_mul_f32_e32 v114, v34, v34
	v_mul_f32_e32 v115, v35, v35
	v_fmac_f32_e32 v112, v36, v36
	v_fmac_f32_e32 v113, v37, v37
	v_fmac_f32_e32 v114, v38, v38
	v_fmac_f32_e32 v115, v39, v39
	v_fmac_f32_e32 v112, v40, v40
	v_fmac_f32_e32 v113, v41, v41
	v_fmac_f32_e32 v114, v42, v42
	v_fmac_f32_e32 v115, v43, v43
	v_fmac_f32_e32 v112, v44, v44
	v_fmac_f32_e32 v113, v45, v45
	v_fmac_f32_e32 v114, v46, v46
	v_fmac_f32_e32 v115, v47, v47
	v_add_f32_e32 v112, v112, v113
	v_add_f32_e32 v114, v114, v115
	v_add_f32_e32 v112, v112, v114
	s_nop 1
	v_add_f32_dpp v112, v112, v112 quad_perm:[1,0,3,2] row_mask:0xf bank_mask:0xf
	s_nop 1
	v_add_f32_dpp v112, v112, v112 quad_perm:[2,3,0,1] row_mask:0xf bank_mask:0xf
	s_nop 1
	v_add_f32_dpp v112, v112, v112 row_half_mirror row_mask:0xf bank_mask:0xf
	s_nop 1
	v_add_f32_dpp v112, v112, v112 row_mirror row_mask:0xf bank_mask:0xf
	s_nop 1
	v_add_f32_dpp v112, v112, v112 row_bcast:15 row_mask:0xa bank_mask:0xf
	s_nop 1
	v_add_f32_dpp v112, v112, v112 row_bcast:31 row_mask:0xc bank_mask:0xf
	s_nop 1
	v_readlane_b32 s2, v112, 63
	s_nop 1
	v_mov_b32_e32 v113, 0x358637bd
	v_mov_b32_e32 v114, 0x3a800000
	v_fmac_f32_e32 v113, s2, v114
	v_rsq_f32_e32 v115, v113
	v_mul_f32_e32 v113, 0.5, v113
	v_mul_f32_e32 v116, v115, v115
	v_mov_b32_e32 v117, 0x3fc00000
	v_fma_f32 v116, -v113, v116, v117
	v_mul_f32_e32 v144, v115, v116
	v_pk_mul_f32 v[32:33], v[32:33], v[144:145] op_sel_hi:[1,0]
	v_pk_mul_f32 v[34:35], v[34:35], v[144:145] op_sel_hi:[1,0]
	v_pk_mul_f32 v[36:37], v[36:37], v[144:145] op_sel_hi:[1,0]
	v_pk_mul_f32 v[38:39], v[38:39], v[144:145] op_sel_hi:[1,0]
	v_pk_mul_f32 v[40:41], v[40:41], v[144:145] op_sel_hi:[1,0]
	v_pk_mul_f32 v[42:43], v[42:43], v[144:145] op_sel_hi:[1,0]
	v_pk_mul_f32 v[44:45], v[44:45], v[144:145] op_sel_hi:[1,0]
	v_pk_mul_f32 v[46:47], v[46:47], v[144:145] op_sel_hi:[1,0]
	v_pk_fma_f32 v[32:33], v[64:65], v[32:33], v[48:49]
	v_pk_fma_f32 v[34:35], v[66:67], v[34:35], v[50:51]
	v_pk_fma_f32 v[36:37], v[68:69], v[36:37], v[52:53]
	v_pk_fma_f32 v[38:39], v[70:71], v[38:39], v[54:55]
	v_pk_fma_f32 v[40:41], v[72:73], v[40:41], v[56:57]
	v_pk_fma_f32 v[42:43], v[74:75], v[42:43], v[58:59]
	v_pk_fma_f32 v[44:45], v[76:77], v[44:45], v[60:61]
	v_pk_fma_f32 v[46:47], v[78:79], v[46:47], v[62:63]
	v_cvt_pk_bf16_f32 v120, v32, v33
	v_cvt_pk_bf16_f32 v121, v34, v35
	v_cvt_pk_bf16_f32 v122, v36, v37
	v_cvt_pk_bf16_f32 v123, v38, v39
	v_cvt_pk_bf16_f32 v124, v40, v41
	v_cvt_pk_bf16_f32 v125, v42, v43
	v_cvt_pk_bf16_f32 v126, v44, v45
	v_cvt_pk_bf16_f32 v127, v46, v47
	v_cndmask_b32_e64 v112, v122, v120, s[40:41]
	v_cndmask_b32_e64 v113, v123, v121, s[40:41]
	v_cndmask_b32_e64 v114, v126, v124, s[40:41]
	v_cndmask_b32_e64 v115, v127, v125, s[40:41]
	v_mov_b32_dpp v116, v112 quad_perm:[1,0,3,2] row_mask:0xf bank_mask:0xf
	v_mov_b32_dpp v117, v113 quad_perm:[1,0,3,2] row_mask:0xf bank_mask:0xf
	v_mov_b32_dpp v118, v114 quad_perm:[1,0,3,2] row_mask:0xf bank_mask:0xf
	v_mov_b32_dpp v119, v115 quad_perm:[1,0,3,2] row_mask:0xf bank_mask:0xf
	s_nop 0
	v_cndmask_b32_e64 v160, v120, v116, s[40:41]
	v_cndmask_b32_e64 v161, v121, v117, s[40:41]
	v_cndmask_b32_e64 v162, v116, v122, s[40:41]
	v_cndmask_b32_e64 v163, v117, v123, s[40:41]
	v_cndmask_b32_e64 v164, v124, v118, s[40:41]
	v_cndmask_b32_e64 v165, v125, v119, s[40:41]
	v_cndmask_b32_e64 v166, v118, v126, s[40:41]
	v_cndmask_b32_e64 v167, v119, v127, s[40:41]
	global_store_dwordx4 v[132:133], v[160:163], off sc1
	global_store_dwordx4 v[132:133], v[164:167], off offset:1024 sc1
	v_lshl_add_u64 v[132:133], v[132:133], 0, v[154:155]
	s_add_i32 s0, s0, 1
	s_cmp_lt_i32 s0, 3
	s_cbranch_scc1 .Lln1a_loop
	s_branch .LBB0_438

.Lln1b_loop:
	global_load_dwordx4 v[32:35], v[128:129], off nt
	global_load_dwordx4 v[36:39], v[128:129], off offset:1024 nt
	global_load_dwordx4 v[40:43], v[128:129], off offset:2048 nt
	global_load_dwordx4 v[44:47], v[128:129], off offset:3072 nt
	v_lshl_add_u64 v[128:129], v[128:129], 0, v[152:153]
	s_waitcnt vmcnt(16)
	v_add_f32_e32 v112, v0, v1
	v_add_f32_e32 v113, v2, v3
	v_add_f32_e32 v114, v4, v5
	v_add_f32_e32 v115, v6, v7
	v_add_f32_e32 v116, v8, v9
	v_add_f32_e32 v117, v10, v11
	v_add_f32_e32 v118, v12, v13
	v_add_f32_e32 v119, v14, v15
	v_add_f32_e32 v112, v112, v116
	v_add_f32_e32 v113, v113, v117
	v_add_f32_e32 v114, v114, v118
	v_add_f32_e32 v115, v115, v119
	v_add_f32_e32 v112, v112, v113
	v_add_f32_e32 v114, v114, v115
	v_add_f32_e32 v112, v112, v114
	s_nop 1
	v_add_f32_dpp v112, v112, v112 quad_perm:[1,0,3,2] row_mask:0xf bank_mask:0xf
	s_nop 1
	v_add_f32_dpp v112, v112, v112 quad_perm:[2,3,0,1] row_mask:0xf bank_mask:0xf
	s_nop 1
	v_add_f32_dpp v112, v112, v112 row_half_mirror row_mask:0xf bank_mask:0xf
	s_nop 1
	v_add_f32_dpp v112, v112, v112 row_mirror row_mask:0xf bank_mask:0xf
	s_nop 1
	v_add_f32_dpp v112, v112, v112 row_bcast:15 row_mask:0xa bank_mask:0xf
	s_nop 1
	v_add_f32_dpp v112, v112, v112 row_bcast:31 row_mask:0xc bank_mask:0xf
	s_nop 1
	v_readlane_b32 s2, v112, 63
	s_nop 1
	v_fmac_f32_e32 v0, s2, v142
	v_fmac_f32_e32 v1, s2, v142
	v_fmac_f32_e32 v2, s2, v142
	v_fmac_f32_e32 v3, s2, v142
	v_fmac_f32_e32 v4, s2, v142
	v_fmac_f32_e32 v5, s2, v142
	v_fmac_f32_e32 v6, s2, v142
	v_fmac_f32_e32 v7, s2, v142
	v_fmac_f32_e32 v8, s2, v142
	v_fmac_f32_e32 v9, s2, v142
	v_fmac_f32_e32 v10, s2, v142
	v_fmac_f32_e32 v11, s2, v142
	v_fmac_f32_e32 v12, s2, v142
	v_fmac_f32_e32 v13, s2, v142
	v_fmac_f32_e32 v14, s2, v142
	v_fmac_f32_e32 v15, s2, v142
	v_mul_f32_e32 v112, v0, v0
	v_mul_f32_e32 v113, v1, v1
	v_mul_f32_e32 v114, v2, v2
	v_mul_f32_e32 v115, v3, v3
	v_fmac_f32_e32 v112, v4, v4
	v_fmac_f32_e32 v113, v5, v5
	v_fmac_f32_e32 v114, v6, v6
	v_fmac_f32_e32 v115, v7, v7
	v_fmac_f32_e32 v112, v8, v8
	v_fmac_f32_e32 v113, v9, v9
	v_fmac_f32_e32 v114, v10, v10
	v_fmac_f32_e32 v115, v11, v11
	v_fmac_f32_e32 v112, v12, v12
	v_fmac_f32_e32 v113, v13, v13
	v_fmac_f32_e32 v114, v14, v14
	v_fmac_f32_e32 v115, v15, v15
	v_add_f32_e32 v112, v112, v113
	v_add_f32_e32 v114, v114, v115
	v_add_f32_e32 v112, v112, v114
	s_nop 1
	v_add_f32_dpp v112, v112, v112 quad_perm:[1,0,3,2] row_mask:0xf bank_mask:0xf
	s_nop 1
	v_add_f32_dpp v112, v112, v112 quad_perm:[2,3,0,1] row_mask:0xf bank_mask:0xf
	s_nop 1
	v_add_f32_dpp v112, v112, v112 row_half_mirror row_mask:0xf bank_mask:0xf
	s_nop 1
	v_add_f32_dpp v112, v112, v112 row_mirror row_mask:0xf bank_mask:0xf
	s_nop 1
	v_add_f32_dpp v112, v112, v112 row_bcast:15 row_mask:0xa bank_mask:0xf
	s_nop 1
	v_add_f32_dpp v112, v112, v112 row_bcast:31 row_mask:0xc bank_mask:0xf
	s_nop 1
	v_readlane_b32 s2, v112, 63
	s_nop 1
	v_mov_b32_e32 v113, 0x358637bd
	v_mov_b32_e32 v114, 0x3a800000
	v_fmac_f32_e32 v113, s2, v114
	v_rsq_f32_e32 v115, v113
	v_mul_f32_e32 v113, 0.5, v113
	v_mul_f32_e32 v116, v115, v115
	v_mov_b32_e32 v117, 0x3fc00000
	v_fma_f32 v116, -v113, v116, v117
	v_mul_f32_e32 v144, v115, v116
	v_pk_mul_f32 v[0:1], v[0:1], v[144:145] op_sel_hi:[1,0]
	v_pk_mul_f32 v[2:3], v[2:3], v[144:145] op_sel_hi:[1,0]
	v_pk_mul_f32 v[4:5], v[4:5], v[144:145] op_sel_hi:[1,0]
	v_pk_mul_f32 v[6:7], v[6:7], v[144:145] op_sel_hi:[1,0]
	v_pk_mul_f32 v[8:9], v[8:9], v[144:145] op_sel_hi:[1,0]
	v_pk_mul_f32 v[10:11], v[10:11], v[144:145] op_sel_hi:[1,0]
	v_pk_mul_f32 v[12:13], v[12:13], v[144:145] op_sel_hi:[1,0]
	v_pk_mul_f32 v[14:15], v[14:15], v[144:145] op_sel_hi:[1,0]
	v_pk_fma_f32 v[0:1], v[80:81], v[0:1], v[96:97]
	v_pk_fma_f32 v[2:3], v[82:83], v[2:3], v[98:99]
	v_pk_fma_f32 v[4:5], v[84:85], v[4:5], v[100:101]
	v_pk_fma_f32 v[6:7], v[86:87], v[6:7], v[102:103]
	v_pk_fma_f32 v[8:9], v[88:89], v[8:9], v[104:105]
	v_pk_fma_f32 v[10:11], v[90:91], v[10:11], v[106:107]
	v_pk_fma_f32 v[12:13], v[92:93], v[12:13], v[108:109]
	v_pk_fma_f32 v[14:15], v[94:95], v[14:15], v[110:111]
	global_store_dwordx4 v[130:131], v[0:3], off sc1
	global_store_dwordx4 v[130:131], v[4:7], off offset:1024 sc1
	global_store_dwordx4 v[130:131], v[8:11], off offset:2048 sc1
	global_store_dwordx4 v[130:131], v[12:15], off offset:3072 sc1
	v_lshl_add_u64 v[130:131], v[130:131], 0, v[152:153]
	global_load_dwordx4 v[0:3], v[128:129], off nt
	global_load_dwordx4 v[4:7], v[128:129], off offset:1024 nt
	global_load_dwordx4 v[8:11], v[128:129], off offset:2048 nt
	global_load_dwordx4 v[12:15], v[128:129], off offset:3072 nt
	v_lshl_add_u64 v[128:129], v[128:129], 0, v[152:153]
	s_waitcnt vmcnt(16)
	v_add_f32_e32 v112, v16, v17
	v_add_f32_e32 v113, v18, v19
	v_add_f32_e32 v114, v20, v21
	v_add_f32_e32 v115, v22, v23
	v_add_f32_e32 v116, v24, v25
	v_add_f32_e32 v117, v26, v27
	v_add_f32_e32 v118, v28, v29
	v_add_f32_e32 v119, v30, v31
	v_add_f32_e32 v112, v112, v116
	v_add_f32_e32 v113, v113, v117
	v_add_f32_e32 v114, v114, v118
	v_add_f32_e32 v115, v115, v119
	v_add_f32_e32 v112, v112, v113
	v_add_f32_e32 v114, v114, v115
	v_add_f32_e32 v112, v112, v114
	s_nop 1
	v_add_f32_dpp v112, v112, v112 quad_perm:[1,0,3,2] row_mask:0xf bank_mask:0xf
	s_nop 1
	v_add_f32_dpp v112, v112, v112 quad_perm:[2,3,0,1] row_mask:0xf bank_mask:0xf
	s_nop 1
	v_add_f32_dpp v112, v112, v112 row_half_mirror row_mask:0xf bank_mask:0xf
	s_nop 1
	v_add_f32_dpp v112, v112, v112 row_mirror row_mask:0xf bank_mask:0xf
	s_nop 1
	v_add_f32_dpp v112, v112, v112 row_bcast:15 row_mask:0xa bank_mask:0xf
	s_nop 1
	v_add_f32_dpp v112, v112, v112 row_bcast:31 row_mask:0xc bank_mask:0xf
	s_nop 1
	v_readlane_b32 s2, v112, 63
	s_nop 1
	v_fmac_f32_e32 v16, s2, v142
	v_fmac_f32_e32 v17, s2, v142
	v_fmac_f32_e32 v18, s2, v142
	v_fmac_f32_e32 v19, s2, v142
	v_fmac_f32_e32 v20, s2, v142
	v_fmac_f32_e32 v21, s2, v142
	v_fmac_f32_e32 v22, s2, v142
	v_fmac_f32_e32 v23, s2, v142
	v_fmac_f32_e32 v24, s2, v142
	v_fmac_f32_e32 v25, s2, v142
	v_fmac_f32_e32 v26, s2, v142
	v_fmac_f32_e32 v27, s2, v142
	v_fmac_f32_e32 v28, s2, v142
	v_fmac_f32_e32 v29, s2, v142
	v_fmac_f32_e32 v30, s2, v142
	v_fmac_f32_e32 v31, s2, v142
	v_mul_f32_e32 v112, v16, v16
	v_mul_f32_e32 v113, v17, v17
	v_mul_f32_e32 v114, v18, v18
	v_mul_f32_e32 v115, v19, v19
	v_fmac_f32_e32 v112, v20, v20
	v_fmac_f32_e32 v113, v21, v21
	v_fmac_f32_e32 v114, v22, v22
	v_fmac_f32_e32 v115, v23, v23
	v_fmac_f32_e32 v112, v24, v24
	v_fmac_f32_e32 v113, v25, v25
	v_fmac_f32_e32 v114, v26, v26
	v_fmac_f32_e32 v115, v27, v27
	v_fmac_f32_e32 v112, v28, v28
	v_fmac_f32_e32 v113, v29, v29
	v_fmac_f32_e32 v114, v30, v30
	v_fmac_f32_e32 v115, v31, v31
	v_add_f32_e32 v112, v112, v113
	v_add_f32_e32 v114, v114, v115
	v_add_f32_e32 v112, v112, v114
	s_nop 1
	v_add_f32_dpp v112, v112, v112 quad_perm:[1,0,3,2] row_mask:0xf bank_mask:0xf
	s_nop 1
	v_add_f32_dpp v112, v112, v112 quad_perm:[2,3,0,1] row_mask:0xf bank_mask:0xf
	s_nop 1
	v_add_f32_dpp v112, v112, v112 row_half_mirror row_mask:0xf bank_mask:0xf
	s_nop 1
	v_add_f32_dpp v112, v112, v112 row_mirror row_mask:0xf bank_mask:0xf
	s_nop 1
	v_add_f32_dpp v112, v112, v112 row_bcast:15 row_mask:0xa bank_mask:0xf
	s_nop 1
	v_add_f32_dpp v112, v112, v112 row_bcast:31 row_mask:0xc bank_mask:0xf
	s_nop 1
	v_readlane_b32 s2, v112, 63
	s_nop 1
	v_mov_b32_e32 v113, 0x358637bd
	v_mov_b32_e32 v114, 0x3a800000
	v_fmac_f32_e32 v113, s2, v114
	v_rsq_f32_e32 v115, v113
	v_mul_f32_e32 v113, 0.5, v113
	v_mul_f32_e32 v116, v115, v115
	v_mov_b32_e32 v117, 0x3fc00000
	v_fma_f32 v116, -v113, v116, v117
	v_mul_f32_e32 v144, v115, v116
	v_pk_mul_f32 v[16:17], v[16:17], v[144:145] op_sel_hi:[1,0]
	v_pk_mul_f32 v[18:19], v[18:19], v[144:145] op_sel_hi:[1,0]
	v_pk_mul_f32 v[20:21], v[20:21], v[144:145] op_sel_hi:[1,0]
	v_pk_mul_f32 v[22:23], v[22:23], v[144:145] op_sel_hi:[1,0]
	v_pk_mul_f32 v[24:25], v[24:25], v[144:145] op_sel_hi:[1,0]
	v_pk_mul_f32 v[26:27], v[26:27], v[144:145] op_sel_hi:[1,0]
	v_pk_mul_f32 v[28:29], v[28:29], v[144:145] op_sel_hi:[1,0]
	v_pk_mul_f32 v[30:31], v[30:31], v[144:145] op_sel_hi:[1,0]
	v_pk_fma_f32 v[16:17], v[80:81], v[16:17], v[96:97]
	v_pk_fma_f32 v[18:19], v[82:83], v[18:19], v[98:99]
	v_pk_fma_f32 v[20:21], v[84:85], v[20:21], v[100:101]
	v_pk_fma_f32 v[22:23], v[86:87], v[22:23], v[102:103]
	v_pk_fma_f32 v[24:25], v[88:89], v[24:25], v[104:105]
	v_pk_fma_f32 v[26:27], v[90:91], v[26:27], v[106:107]
	v_pk_fma_f32 v[28:29], v[92:93], v[28:29], v[108:109]
	v_pk_fma_f32 v[30:31], v[94:95], v[30:31], v[110:111]
	global_store_dwordx4 v[130:131], v[16:19], off sc1
	global_store_dwordx4 v[130:131], v[20:23], off offset:1024 sc1
	global_store_dwordx4 v[130:131], v[24:27], off offset:2048 sc1
	global_store_dwordx4 v[130:131], v[28:31], off offset:3072 sc1
	v_lshl_add_u64 v[130:131], v[130:131], 0, v[152:153]
	global_load_dwordx4 v[16:19], v[128:129], off nt
	global_load_dwordx4 v[20:23], v[128:129], off offset:1024 nt
	global_load_dwordx4 v[24:27], v[128:129], off offset:2048 nt
	global_load_dwordx4 v[28:31], v[128:129], off offset:3072 nt
	v_lshl_add_u64 v[128:129], v[128:129], 0, v[152:153]
	s_waitcnt vmcnt(16)
	v_add_f32_e32 v112, v32, v33
	v_add_f32_e32 v113, v34, v35
	v_add_f32_e32 v114, v36, v37
	v_add_f32_e32 v115, v38, v39
	v_add_f32_e32 v116, v40, v41
	v_add_f32_e32 v117, v42, v43
	v_add_f32_e32 v118, v44, v45
	v_add_f32_e32 v119, v46, v47
	v_add_f32_e32 v112, v112, v116
	v_add_f32_e32 v113, v113, v117
	v_add_f32_e32 v114, v114, v118
	v_add_f32_e32 v115, v115, v119
	v_add_f32_e32 v112, v112, v113
	v_add_f32_e32 v114, v114, v115
	v_add_f32_e32 v112, v112, v114
	s_nop 1
	v_add_f32_dpp v112, v112, v112 quad_perm:[1,0,3,2] row_mask:0xf bank_mask:0xf
	s_nop 1
	v_add_f32_dpp v112, v112, v112 quad_perm:[2,3,0,1] row_mask:0xf bank_mask:0xf
	s_nop 1
	v_add_f32_dpp v112, v112, v112 row_half_mirror row_mask:0xf bank_mask:0xf
	s_nop 1
	v_add_f32_dpp v112, v112, v112 row_mirror row_mask:0xf bank_mask:0xf
	s_nop 1
	v_add_f32_dpp v112, v112, v112 row_bcast:15 row_mask:0xa bank_mask:0xf
	s_nop 1
	v_add_f32_dpp v112, v112, v112 row_bcast:31 row_mask:0xc bank_mask:0xf
	s_nop 1
	v_readlane_b32 s2, v112, 63
	s_nop 1
	v_fmac_f32_e32 v32, s2, v142
	v_fmac_f32_e32 v33, s2, v142
	v_fmac_f32_e32 v34, s2, v142
	v_fmac_f32_e32 v35, s2, v142
	v_fmac_f32_e32 v36, s2, v142
	v_fmac_f32_e32 v37, s2, v142
	v_fmac_f32_e32 v38, s2, v142
	v_fmac_f32_e32 v39, s2, v142
	v_fmac_f32_e32 v40, s2, v142
	v_fmac_f32_e32 v41, s2, v142
	v_fmac_f32_e32 v42, s2, v142
	v_fmac_f32_e32 v43, s2, v142
	v_fmac_f32_e32 v44, s2, v142
	v_fmac_f32_e32 v45, s2, v142
	v_fmac_f32_e32 v46, s2, v142
	v_fmac_f32_e32 v47, s2, v142
	v_mul_f32_e32 v112, v32, v32
	v_mul_f32_e32 v113, v33, v33
	v_mul_f32_e32 v114, v34, v34
	v_mul_f32_e32 v115, v35, v35
	v_fmac_f32_e32 v112, v36, v36
	v_fmac_f32_e32 v113, v37, v37
	v_fmac_f32_e32 v114, v38, v38
	v_fmac_f32_e32 v115, v39, v39
	v_fmac_f32_e32 v112, v40, v40
	v_fmac_f32_e32 v113, v41, v41
	v_fmac_f32_e32 v114, v42, v42
	v_fmac_f32_e32 v115, v43, v43
	v_fmac_f32_e32 v112, v44, v44
	v_fmac_f32_e32 v113, v45, v45
	v_fmac_f32_e32 v114, v46, v46
	v_fmac_f32_e32 v115, v47, v47
	v_add_f32_e32 v112, v112, v113
	v_add_f32_e32 v114, v114, v115
	v_add_f32_e32 v112, v112, v114
	s_nop 1
	v_add_f32_dpp v112, v112, v112 quad_perm:[1,0,3,2] row_mask:0xf bank_mask:0xf
	s_nop 1
	v_add_f32_dpp v112, v112, v112 quad_perm:[2,3,0,1] row_mask:0xf bank_mask:0xf
	s_nop 1
	v_add_f32_dpp v112, v112, v112 row_half_mirror row_mask:0xf bank_mask:0xf
	s_nop 1
	v_add_f32_dpp v112, v112, v112 row_mirror row_mask:0xf bank_mask:0xf
	s_nop 1
	v_add_f32_dpp v112, v112, v112 row_bcast:15 row_mask:0xa bank_mask:0xf
	s_nop 1
	v_add_f32_dpp v112, v112, v112 row_bcast:31 row_mask:0xc bank_mask:0xf
	s_nop 1
	v_readlane_b32 s2, v112, 63
	s_nop 1
	v_mov_b32_e32 v113, 0x358637bd
	v_mov_b32_e32 v114, 0x3a800000
	v_fmac_f32_e32 v113, s2, v114
	v_rsq_f32_e32 v115, v113
	v_mul_f32_e32 v113, 0.5, v113
	v_mul_f32_e32 v116, v115, v115
	v_mov_b32_e32 v117, 0x3fc00000
	v_fma_f32 v116, -v113, v116, v117
	v_mul_f32_e32 v144, v115, v116
	v_pk_mul_f32 v[32:33], v[32:33], v[144:145] op_sel_hi:[1,0]
	v_pk_mul_f32 v[34:35], v[34:35], v[144:145] op_sel_hi:[1,0]
	v_pk_mul_f32 v[36:37], v[36:37], v[144:145] op_sel_hi:[1,0]
	v_pk_mul_f32 v[38:39], v[38:39], v[144:145] op_sel_hi:[1,0]
	v_pk_mul_f32 v[40:41], v[40:41], v[144:145] op_sel_hi:[1,0]
	v_pk_mul_f32 v[42:43], v[42:43], v[144:145] op_sel_hi:[1,0]
	v_pk_mul_f32 v[44:45], v[44:45], v[144:145] op_sel_hi:[1,0]
	v_pk_mul_f32 v[46:47], v[46:47], v[144:145] op_sel_hi:[1,0]
	v_pk_fma_f32 v[32:33], v[80:81], v[32:33], v[96:97]
	v_pk_fma_f32 v[34:35], v[82:83], v[34:35], v[98:99]
	v_pk_fma_f32 v[36:37], v[84:85], v[36:37], v[100:101]
	v_pk_fma_f32 v[38:39], v[86:87], v[38:39], v[102:103]
	v_pk_fma_f32 v[40:41], v[88:89], v[40:41], v[104:105]
	v_pk_fma_f32 v[42:43], v[90:91], v[42:43], v[106:107]
	v_pk_fma_f32 v[44:45], v[92:93], v[44:45], v[108:109]
	v_pk_fma_f32 v[46:47], v[94:95], v[46:47], v[110:111]
	global_store_dwordx4 v[130:131], v[32:35], off sc1
	global_store_dwordx4 v[130:131], v[36:39], off offset:1024 sc1
	global_store_dwordx4 v[130:131], v[40:43], off offset:2048 sc1
	global_store_dwordx4 v[130:131], v[44:47], off offset:3072 sc1
	v_lshl_add_u64 v[130:131], v[130:131], 0, v[152:153]
	global_load_dwordx4 v[32:35], v[128:129], off nt
	global_load_dwordx4 v[36:39], v[128:129], off offset:1024 nt
	global_load_dwordx4 v[40:43], v[128:129], off offset:2048 nt
	global_load_dwordx4 v[44:47], v[128:129], off offset:3072 nt
	v_lshl_add_u64 v[128:129], v[128:129], 0, v[152:153]
	s_cmp_lg_u32 s0, 2
	s_cbranch_scc1 .Lln1b_nopark
	v_lshl_add_u64 v[128:129], s[60:61], 0, v[148:149]
.Lln1b_nopark:
	s_waitcnt vmcnt(16)
	v_add_f32_e32 v112, v0, v1
	v_add_f32_e32 v113, v2, v3
	v_add_f32_e32 v114, v4, v5
	v_add_f32_e32 v115, v6, v7
	v_add_f32_e32 v116, v8, v9
	v_add_f32_e32 v117, v10, v11
	v_add_f32_e32 v118, v12, v13
	v_add_f32_e32 v119, v14, v15
	v_add_f32_e32 v112, v112, v116
	v_add_f32_e32 v113, v113, v117
	v_add_f32_e32 v114, v114, v118
	v_add_f32_e32 v115, v115, v119
	v_add_f32_e32 v112, v112, v113
	v_add_f32_e32 v114, v114, v115
	v_add_f32_e32 v112, v112, v114
	s_nop 1
	v_add_f32_dpp v112, v112, v112 quad_perm:[1,0,3,2] row_mask:0xf bank_mask:0xf
	s_nop 1
	v_add_f32_dpp v112, v112, v112 quad_perm:[2,3,0,1] row_mask:0xf bank_mask:0xf
	s_nop 1
	v_add_f32_dpp v112, v112, v112 row_half_mirror row_mask:0xf bank_mask:0xf
	s_nop 1
	v_add_f32_dpp v112, v112, v112 row_mirror row_mask:0xf bank_mask:0xf
	s_nop 1
	v_add_f32_dpp v112, v112, v112 row_bcast:15 row_mask:0xa bank_mask:0xf
	s_nop 1
	v_add_f32_dpp v112, v112, v112 row_bcast:31 row_mask:0xc bank_mask:0xf
	s_nop 1
	v_readlane_b32 s2, v112, 63
	s_nop 1
	v_fmac_f32_e32 v0, s2, v142
	v_fmac_f32_e32 v1, s2, v142
	v_fmac_f32_e32 v2, s2, v142
	v_fmac_f32_e32 v3, s2, v142
	v_fmac_f32_e32 v4, s2, v142
	v_fmac_f32_e32 v5, s2, v142
	v_fmac_f32_e32 v6, s2, v142
	v_fmac_f32_e32 v7, s2, v142
	v_fmac_f32_e32 v8, s2, v142
	v_fmac_f32_e32 v9, s2, v142
	v_fmac_f32_e32 v10, s2, v142
	v_fmac_f32_e32 v11, s2, v142
	v_fmac_f32_e32 v12, s2, v142
	v_fmac_f32_e32 v13, s2, v142
	v_fmac_f32_e32 v14, s2, v142
	v_fmac_f32_e32 v15, s2, v142
	v_mul_f32_e32 v112, v0, v0
	v_mul_f32_e32 v113, v1, v1
	v_mul_f32_e32 v114, v2, v2
	v_mul_f32_e32 v115, v3, v3
	v_fmac_f32_e32 v112, v4, v4
	v_fmac_f32_e32 v113, v5, v5
	v_fmac_f32_e32 v114, v6, v6
	v_fmac_f32_e32 v115, v7, v7
	v_fmac_f32_e32 v112, v8, v8
	v_fmac_f32_e32 v113, v9, v9
	v_fmac_f32_e32 v114, v10, v10
	v_fmac_f32_e32 v115, v11, v11
	v_fmac_f32_e32 v112, v12, v12
	v_fmac_f32_e32 v113, v13, v13
	v_fmac_f32_e32 v114, v14, v14
	v_fmac_f32_e32 v115, v15, v15
	v_add_f32_e32 v112, v112, v113
	v_add_f32_e32 v114, v114, v115
	v_add_f32_e32 v112, v112, v114
	s_nop 1
	v_add_f32_dpp v112, v112, v112 quad_perm:[1,0,3,2] row_mask:0xf bank_mask:0xf
	s_nop 1
	v_add_f32_dpp v112, v112, v112 quad_perm:[2,3,0,1] row_mask:0xf bank_mask:0xf
	s_nop 1
	v_add_f32_dpp v112, v112, v112 row_half_mirror row_mask:0xf bank_mask:0xf
	s_nop 1
	v_add_f32_dpp v112, v112, v112 row_mirror row_mask:0xf bank_mask:0xf
	s_nop 1
	v_add_f32_dpp v112, v112, v112 row_bcast:15 row_mask:0xa bank_mask:0xf
	s_nop 1
	v_add_f32_dpp v112, v112, v112 row_bcast:31 row_mask:0xc bank_mask:0xf
	s_nop 1
	v_readlane_b32 s2, v112, 63
	s_nop 1
	v_mov_b32_e32 v113, 0x358637bd
	v_mov_b32_e32 v114, 0x3a800000
	v_fmac_f32_e32 v113, s2, v114
	v_rsq_f32_e32 v115, v113
	v_mul_f32_e32 v113, 0.5, v113
	v_mul_f32_e32 v116, v115, v115
	v_mov_b32_e32 v117, 0x3fc00000
	v_fma_f32 v116, -v113, v116, v117
	v_mul_f32_e32 v144, v115, v116
	v_pk_mul_f32 v[0:1], v[0:1], v[144:145] op_sel_hi:[1,0]
	v_pk_mul_f32 v[2:3], v[2:3], v[144:145] op_sel_hi:[1,0]
	v_pk_mul_f32 v[4:5], v[4:5], v[144:145] op_sel_hi:[1,0]
	v_pk_mul_f32 v[6:7], v[6:7], v[144:145] op_sel_hi:[1,0]
	v_pk_mul_f32 v[8:9], v[8:9], v[144:145] op_sel_hi:[1,0]
	v_pk_mul_f32 v[10:11], v[10:11], v[144:145] op_sel_hi:[1,0]
	v_pk_mul_f32 v[12:13], v[12:13], v[144:145] op_sel_hi:[1,0]
	v_pk_mul_f32 v[14:15], v[14:15], v[144:145] op_sel_hi:[1,0]
	v_pk_fma_f32 v[0:1], v[80:81], v[0:1], v[96:97]
	v_pk_fma_f32 v[2:3], v[82:83], v[2:3], v[98:99]
	v_pk_fma_f32 v[4:5], v[84:85], v[4:5], v[100:101]
	v_pk_fma_f32 v[6:7], v[86:87], v[6:7], v[102:103]
	v_pk_fma_f32 v[8:9], v[88:89], v[8:9], v[104:105]
	v_pk_fma_f32 v[10:11], v[90:91], v[10:11], v[106:107]
	v_pk_fma_f32 v[12:13], v[92:93], v[12:13], v[108:109]
	v_pk_fma_f32 v[14:15], v[94:95], v[14:15], v[110:111]
	global_store_dwordx4 v[130:131], v[0:3], off sc1
	global_store_dwordx4 v[130:131], v[4:7], off offset:1024 sc1
	global_store_dwordx4 v[130:131], v[8:11], off offset:2048 sc1
	global_store_dwordx4 v[130:131], v[12:15], off offset:3072 sc1
	v_lshl_add_u64 v[130:131], v[130:131], 0, v[152:153]
	global_load_dwordx4 v[0:3], v[128:129], off nt
	global_load_dwordx4 v[4:7], v[128:129], off offset:1024 nt
	global_load_dwordx4 v[8:11], v[128:129], off offset:2048 nt
	global_load_dwordx4 v[12:15], v[128:129], off offset:3072 nt
	v_lshl_add_u64 v[128:129], v[128:129], 0, v[152:153]
	s_waitcnt vmcnt(16)
	v_add_f32_e32 v112, v16, v17
	v_add_f32_e32 v113, v18, v19
	v_add_f32_e32 v114, v20, v21
	v_add_f32_e32 v115, v22, v23
	v_add_f32_e32 v116, v24, v25
	v_add_f32_e32 v117, v26, v27
	v_add_f32_e32 v118, v28, v29
	v_add_f32_e32 v119, v30, v31
	v_add_f32_e32 v112, v112, v116
	v_add_f32_e32 v113, v113, v117
	v_add_f32_e32 v114, v114, v118
	v_add_f32_e32 v115, v115, v119
	v_add_f32_e32 v112, v112, v113
	v_add_f32_e32 v114, v114, v115
	v_add_f32_e32 v112, v112, v114
	s_nop 1
	v_add_f32_dpp v112, v112, v112 quad_perm:[1,0,3,2] row_mask:0xf bank_mask:0xf
	s_nop 1
	v_add_f32_dpp v112, v112, v112 quad_perm:[2,3,0,1] row_mask:0xf bank_mask:0xf
	s_nop 1
	v_add_f32_dpp v112, v112, v112 row_half_mirror row_mask:0xf bank_mask:0xf
	s_nop 1
	v_add_f32_dpp v112, v112, v112 row_mirror row_mask:0xf bank_mask:0xf
	s_nop 1
	v_add_f32_dpp v112, v112, v112 row_bcast:15 row_mask:0xa bank_mask:0xf
	s_nop 1
	v_add_f32_dpp v112, v112, v112 row_bcast:31 row_mask:0xc bank_mask:0xf
	s_nop 1
	v_readlane_b32 s2, v112, 63
	s_nop 1
	v_fmac_f32_e32 v16, s2, v142
	v_fmac_f32_e32 v17, s2, v142
	v_fmac_f32_e32 v18, s2, v142
	v_fmac_f32_e32 v19, s2, v142
	v_fmac_f32_e32 v20, s2, v142
	v_fmac_f32_e32 v21, s2, v142
	v_fmac_f32_e32 v22, s2, v142
	v_fmac_f32_e32 v23, s2, v142
	v_fmac_f32_e32 v24, s2, v142
	v_fmac_f32_e32 v25, s2, v142
	v_fmac_f32_e32 v26, s2, v142
	v_fmac_f32_e32 v27, s2, v142
	v_fmac_f32_e32 v28, s2, v142
	v_fmac_f32_e32 v29, s2, v142
	v_fmac_f32_e32 v30, s2, v142
	v_fmac_f32_e32 v31, s2, v142
	v_mul_f32_e32 v112, v16, v16
	v_mul_f32_e32 v113, v17, v17
	v_mul_f32_e32 v114, v18, v18
	v_mul_f32_e32 v115, v19, v19
	v_fmac_f32_e32 v112, v20, v20
	v_fmac_f32_e32 v113, v21, v21
	v_fmac_f32_e32 v114, v22, v22
	v_fmac_f32_e32 v115, v23, v23
	v_fmac_f32_e32 v112, v24, v24
	v_fmac_f32_e32 v113, v25, v25
	v_fmac_f32_e32 v114, v26, v26
	v_fmac_f32_e32 v115, v27, v27
	v_fmac_f32_e32 v112, v28, v28
	v_fmac_f32_e32 v113, v29, v29
	v_fmac_f32_e32 v114, v30, v30
	v_fmac_f32_e32 v115, v31, v31
	v_add_f32_e32 v112, v112, v113
	v_add_f32_e32 v114, v114, v115
	v_add_f32_e32 v112, v112, v114
	s_nop 1
	v_add_f32_dpp v112, v112, v112 quad_perm:[1,0,3,2] row_mask:0xf bank_mask:0xf
	s_nop 1
	v_add_f32_dpp v112, v112, v112 quad_perm:[2,3,0,1] row_mask:0xf bank_mask:0xf
	s_nop 1
	v_add_f32_dpp v112, v112, v112 row_half_mirror row_mask:0xf bank_mask:0xf
	s_nop 1
	v_add_f32_dpp v112, v112, v112 row_mirror row_mask:0xf bank_mask:0xf
	s_nop 1
	v_add_f32_dpp v112, v112, v112 row_bcast:15 row_mask:0xa bank_mask:0xf
	s_nop 1
	v_add_f32_dpp v112, v112, v112 row_bcast:31 row_mask:0xc bank_mask:0xf
	s_nop 1
	v_readlane_b32 s2, v112, 63
	s_nop 1
	v_mov_b32_e32 v113, 0x358637bd
	v_mov_b32_e32 v114, 0x3a800000
	v_fmac_f32_e32 v113, s2, v114
	v_rsq_f32_e32 v115, v113
	v_mul_f32_e32 v113, 0.5, v113
	v_mul_f32_e32 v116, v115, v115
	v_mov_b32_e32 v117, 0x3fc00000
	v_fma_f32 v116, -v113, v116, v117
	v_mul_f32_e32 v144, v115, v116
	v_pk_mul_f32 v[16:17], v[16:17], v[144:145] op_sel_hi:[1,0]
	v_pk_mul_f32 v[18:19], v[18:19], v[144:145] op_sel_hi:[1,0]
	v_pk_mul_f32 v[20:21], v[20:21], v[144:145] op_sel_hi:[1,0]
	v_pk_mul_f32 v[22:23], v[22:23], v[144:145] op_sel_hi:[1,0]
	v_pk_mul_f32 v[24:25], v[24:25], v[144:145] op_sel_hi:[1,0]
	v_pk_mul_f32 v[26:27], v[26:27], v[144:145] op_sel_hi:[1,0]
	v_pk_mul_f32 v[28:29], v[28:29], v[144:145] op_sel_hi:[1,0]
	v_pk_mul_f32 v[30:31], v[30:31], v[144:145] op_sel_hi:[1,0]
	v_pk_fma_f32 v[16:17], v[80:81], v[16:17], v[96:97]
	v_pk_fma_f32 v[18:19], v[82:83], v[18:19], v[98:99]
	v_pk_fma_f32 v[20:21], v[84:85], v[20:21], v[100:101]
	v_pk_fma_f32 v[22:23], v[86:87], v[22:23], v[102:103]
	v_pk_fma_f32 v[24:25], v[88:89], v[24:25], v[104:105]
	v_pk_fma_f32 v[26:27], v[90:91], v[26:27], v[106:107]
	v_pk_fma_f32 v[28:29], v[92:93], v[28:29], v[108:109]
	v_pk_fma_f32 v[30:31], v[94:95], v[30:31], v[110:111]
	global_store_dwordx4 v[130:131], v[16:19], off sc1
	global_store_dwordx4 v[130:131], v[20:23], off offset:1024 sc1
	global_store_dwordx4 v[130:131], v[24:27], off offset:2048 sc1
	global_store_dwordx4 v[130:131], v[28:31], off offset:3072 sc1
	v_lshl_add_u64 v[130:131], v[130:131], 0, v[152:153]
	global_load_dwordx4 v[16:19], v[128:129], off nt
	global_load_dwordx4 v[20:23], v[128:129], off offset:1024 nt
	global_load_dwordx4 v[24:27], v[128:129], off offset:2048 nt
	global_load_dwordx4 v[28:31], v[128:129], off offset:3072 nt
	v_lshl_add_u64 v[128:129], v[128:129], 0, v[152:153]
	s_waitcnt vmcnt(16)
	v_add_f32_e32 v112, v32, v33
	v_add_f32_e32 v113, v34, v35
	v_add_f32_e32 v114, v36, v37
	v_add_f32_e32 v115, v38, v39
	v_add_f32_e32 v116, v40, v41
	v_add_f32_e32 v117, v42, v43
	v_add_f32_e32 v118, v44, v45
	v_add_f32_e32 v119, v46, v47
	v_add_f32_e32 v112, v112, v116
	v_add_f32_e32 v113, v113, v117
	v_add_f32_e32 v114, v114, v118
	v_add_f32_e32 v115, v115, v119
	v_add_f32_e32 v112, v112, v113
	v_add_f32_e32 v114, v114, v115
	v_add_f32_e32 v112, v112, v114
	s_nop 1
	v_add_f32_dpp v112, v112, v112 quad_perm:[1,0,3,2] row_mask:0xf bank_mask:0xf
	s_nop 1
	v_add_f32_dpp v112, v112, v112 quad_perm:[2,3,0,1] row_mask:0xf bank_mask:0xf
	s_nop 1
	v_add_f32_dpp v112, v112, v112 row_half_mirror row_mask:0xf bank_mask:0xf
	s_nop 1
	v_add_f32_dpp v112, v112, v112 row_mirror row_mask:0xf bank_mask:0xf
	s_nop 1
	v_add_f32_dpp v112, v112, v112 row_bcast:15 row_mask:0xa bank_mask:0xf
	s_nop 1
	v_add_f32_dpp v112, v112, v112 row_bcast:31 row_mask:0xc bank_mask:0xf
	s_nop 1
	v_readlane_b32 s2, v112, 63
	s_nop 1
	v_fmac_f32_e32 v32, s2, v142
	v_fmac_f32_e32 v33, s2, v142
	v_fmac_f32_e32 v34, s2, v142
	v_fmac_f32_e32 v35, s2, v142
	v_fmac_f32_e32 v36, s2, v142
	v_fmac_f32_e32 v37, s2, v142
	v_fmac_f32_e32 v38, s2, v142
	v_fmac_f32_e32 v39, s2, v142
	v_fmac_f32_e32 v40, s2, v142
	v_fmac_f32_e32 v41, s2, v142
	v_fmac_f32_e32 v42, s2, v142
	v_fmac_f32_e32 v43, s2, v142
	v_fmac_f32_e32 v44, s2, v142
	v_fmac_f32_e32 v45, s2, v142
	v_fmac_f32_e32 v46, s2, v142
	v_fmac_f32_e32 v47, s2, v142
	v_mul_f32_e32 v112, v32, v32
	v_mul_f32_e32 v113, v33, v33
	v_mul_f32_e32 v114, v34, v34
	v_mul_f32_e32 v115, v35, v35
	v_fmac_f32_e32 v112, v36, v36
	v_fmac_f32_e32 v113, v37, v37
	v_fmac_f32_e32 v114, v38, v38
	v_fmac_f32_e32 v115, v39, v39
	v_fmac_f32_e32 v112, v40, v40
	v_fmac_f32_e32 v113, v41, v41
	v_fmac_f32_e32 v114, v42, v42
	v_fmac_f32_e32 v115, v43, v43
	v_fmac_f32_e32 v112, v44, v44
	v_fmac_f32_e32 v113, v45, v45
	v_fmac_f32_e32 v114, v46, v46
	v_fmac_f32_e32 v115, v47, v47
	v_add_f32_e32 v112, v112, v113
	v_add_f32_e32 v114, v114, v115
	v_add_f32_e32 v112, v112, v114
	s_nop 1
	v_add_f32_dpp v112, v112, v112 quad_perm:[1,0,3,2] row_mask:0xf bank_mask:0xf
	s_nop 1
	v_add_f32_dpp v112, v112, v112 quad_perm:[2,3,0,1] row_mask:0xf bank_mask:0xf
	s_nop 1
	v_add_f32_dpp v112, v112, v112 row_half_mirror row_mask:0xf bank_mask:0xf
	s_nop 1
	v_add_f32_dpp v112, v112, v112 row_mirror row_mask:0xf bank_mask:0xf
	s_nop 1
	v_add_f32_dpp v112, v112, v112 row_bcast:15 row_mask:0xa bank_mask:0xf
	s_nop 1
	v_add_f32_dpp v112, v112, v112 row_bcast:31 row_mask:0xc bank_mask:0xf
	s_nop 1
	v_readlane_b32 s2, v112, 63
	s_nop 1
	v_mov_b32_e32 v113, 0x358637bd
	v_mov_b32_e32 v114, 0x3a800000
	v_fmac_f32_e32 v113, s2, v114
	v_rsq_f32_e32 v115, v113
	v_mul_f32_e32 v113, 0.5, v113
	v_mul_f32_e32 v116, v115, v115
	v_mov_b32_e32 v117, 0x3fc00000
	v_fma_f32 v116, -v113, v116, v117
	v_mul_f32_e32 v144, v115, v116
	v_pk_mul_f32 v[32:33], v[32:33], v[144:145] op_sel_hi:[1,0]
	v_pk_mul_f32 v[34:35], v[34:35], v[144:145] op_sel_hi:[1,0]
	v_pk_mul_f32 v[36:37], v[36:37], v[144:145] op_sel_hi:[1,0]
	v_pk_mul_f32 v[38:39], v[38:39], v[144:145] op_sel_hi:[1,0]
	v_pk_mul_f32 v[40:41], v[40:41], v[144:145] op_sel_hi:[1,0]
	v_pk_mul_f32 v[42:43], v[42:43], v[144:145] op_sel_hi:[1,0]
	v_pk_mul_f32 v[44:45], v[44:45], v[144:145] op_sel_hi:[1,0]
	v_pk_mul_f32 v[46:47], v[46:47], v[144:145] op_sel_hi:[1,0]
	v_pk_fma_f32 v[32:33], v[80:81], v[32:33], v[96:97]
	v_pk_fma_f32 v[34:35], v[82:83], v[34:35], v[98:99]
	v_pk_fma_f32 v[36:37], v[84:85], v[36:37], v[100:101]
	v_pk_fma_f32 v[38:39], v[86:87], v[38:39], v[102:103]
	v_pk_fma_f32 v[40:41], v[88:89], v[40:41], v[104:105]
	v_pk_fma_f32 v[42:43], v[90:91], v[42:43], v[106:107]
	v_pk_fma_f32 v[44:45], v[92:93], v[44:45], v[108:109]
	v_pk_fma_f32 v[46:47], v[94:95], v[46:47], v[110:111]
	global_store_dwordx4 v[130:131], v[32:35], off sc1
	global_store_dwordx4 v[130:131], v[36:39], off offset:1024 sc1
	global_store_dwordx4 v[130:131], v[40:43], off offset:2048 sc1
	global_store_dwordx4 v[130:131], v[44:47], off offset:3072 sc1
	v_lshl_add_u64 v[130:131], v[130:131], 0, v[152:153]
	s_add_i32 s0, s0, 1
	s_cmp_lt_i32 s0, 3
	s_cbranch_scc1 .Lln1b_loop
